# SwiGLU-up GEMM last (half-empty) round: each of the 128 remaining units is split by rows between two CUs of the same XCD (half the MFMA blocks and half the epilogue each)
# speedup vs baseline: 1.0074x; 1.0074x over previous
; #define PG8_STAGE(bufoff, gbase, voff) do { _Pragma("unroll") for (int _i = 0; _i < 2; ++_i) \
;         __builtin_amdgcn_global_load_lds((const unsigned*)((const char*)(gbase) + (voff)[_i]), (PG8_LAS unsigned*)(lds + (bufoff) + ldsw + _i * 8192), 16, 0, 0); } while (0)
; #define PG8_WAIT_V(n) asm volatile("s_waitcnt vmcnt(" #n ")" ::: "memory")
; #define PG8_BAR __builtin_amdgcn_s_barrier()
; template <class Epi, class Sched, bool ALIGN_EPI = false, bool SP2 = false>
; __device__ __forceinline__ void gemm_phase(PG8_LAS unsigned char* lds, const Gemm g, const Sched& S, const Epi& E) {
;     ...
;     for (int i = 0; i < 2; ++i) { int R, C; stage_rc(tid * 16 + i * 8192, R, C); const int Rb = Epi::PERM ? ((R & ~31) + perm32(R & 31)) : R;
;         voffA[i] = (unsigned)(R * K + C) * 2u; voffB[i] = (unsigned)(Rb * K + C) * 2u; }
;     const size_t kstep = (size_t)(BK * 2);
;     const size_t hstep = (size_t)HALF * K * 2;
;     const size_t tstep = 2 * hstep;
;     const unsigned ldsw = (unsigned)wid * 1024u;
;     const int aoff = lds_byte(wr * 64 + fr, fq * 8), boff = lds_byte(wc * 32 + fr, fq * 8);
;     ...
;     if constexpr (SP2) {
;         PG8_STAGE(PG8_SB(0, 0), cB, voffB); PG8_STAGE(PG8_SB(0, 1), cB + hstep, voffB); PG8_STAGE(PG8_SA(0, 0), cA, voffA); PG8_STAGE(PG8_SA(0, 1), cA + hstep, voffA);
;         if (wr == 1) PG8_BAR;
;         PG8_WAIT_V(2); PG8_BAR;
;         PG8_STAGE(PG8_SB(1, 0), cB + kstep, voffB); PG8_STAGE(PG8_SA(1, 0), cA + kstep, voffA); PG8_STAGE(PG8_SB(1, 1), cB + hstep + kstep, voffB);
;         PG8_WAIT_V(6); PG8_BAR;
.LBB0_1472:
	s_lshl_b32 s9, s12, 5
	s_mov_b64 s[12:13], 0x80
	s_and_b32 s30, s9, 0x60
	s_add_i32 m0, s31, 0x18000
	v_lshl_add_u64 v[6:7], v[6:7], 0, s[12:13]
	s_lshl_b32 s21, s20, 13
	s_lshl_b32 s38, s30, 7
	s_waitcnt vmcnt(2)
	s_barrier
	global_load_lds_dwordx4 v[6:7], off
	v_lshl_add_u64 v[4:5], v[4:5], 0, s[12:13]
	s_add_i32 m0, s31, 0x1a000
	s_add_i32 s45, s31, 0x8000
	s_add_i32 s52, s31, 0xa000
	global_load_lds_dwordx4 v[4:5], off
	v_lshl_add_u64 v[0:1], v[0:1], 0, s[12:13]
	s_mov_b32 m0, s45
	s_add_u32 s36, s48, 0x40080
	global_load_lds_dwordx4 v[0:1], off
	v_lshl_add_u64 v[0:1], v[2:3], 0, s[12:13]
	s_mov_b32 m0, s52
	s_addc_u32 s37, s49, 0
	global_load_lds_dwordx4 v[0:1], off
	s_add_i32 m0, s31, 0x1c000
	v_lshl_add_u64 v[0:1], s[36:37], 0, v[132:133]
	global_load_lds_dwordx4 v[0:1], off
	v_lshl_add_u64 v[0:1], s[36:37], 0, v[128:129]
	s_add_i32 m0, s31, 0x1e000
	s_cmpk_lt_u32 s7, 0x100
	global_load_lds_dwordx4 v[0:1], off
	v_lshrrev_b32_e32 v1, 1, v10
	v_and_b32_e32 v1, 24, v1
	v_and_b32_e32 v0, 15, v10
	v_lshlrev_b32_e32 v2, 1, v1
	v_lshl_or_b32 v150, s20, 6, v0
	v_lshl_or_b32 v0, v0, 6, v2
	v_lshlrev_b32_e32 v2, 2, v10
	v_and_b32_e32 v2, 32, v2
	v_bitop3_b32 v3, v0, s21, v2 bitop3:0xde
	v_bitop3_b32 v151, v0, s38, v2 bitop3:0xde
	v_lshlrev_b32_e32 v0, 14, v13
	v_and_b32_e32 v0, 0xffff8000, v0
	v_or_b32_e32 v152, s30, v1
	v_lshl_add_u32 v0, v12, 11, v0
	v_and_b32_e32 v1, 1, v13
	v_lshl_or_b32 v0, v1, 6, v0
	v_lshl_add_u32 v136, v14, 1, v0
	v_lshlrev_b32_e32 v0, 14, v8
	v_and_b32_e32 v0, 0xffff8000, v0
	s_waitcnt vmcnt(6)
	v_lshl_add_u32 v0, v9, 11, v0
	v_and_b32_e32 v1, 1, v8
	s_cselect_b64 s[20:21], -1, 0
	v_lshl_or_b32 v0, v1, 6, v0
	s_add_i32 s55, 0, 0x10000
	s_add_i32 s56, 0, 0x14000
	s_sext_i32_i16 s9, s6
	s_ashr_i32 s53, s86, 31
	s_mov_b32 s54, s86
	v_mov_b32_e32 v137, v133
	v_lshl_add_u32 v138, v11, 1, v0
	v_mov_b32_e32 v139, v133
	v_mov_b64_e32 v[140:141], 0x580
	v_mov_b64_e32 v[142:143], 0x57f
	v_add_u32_e32 v153, s55, v151
	v_add_u32_e32 v159, s56, v151
	v_add_u32_e32 v160, 0, v3
	v_mov_b32_e32 v161, 0x358637bd
	s_mov_b32 s57, 0x800000
	s_movk_i32 s58, 0x1600
	s_barrier
	s_mov_b32 s98, 0
	s_mov_b32 s101, 0
	s_branch .LBB0_1475

;     __host__ __device__ bool next(int i, Unit& u) const {
;         const long L = (long)i * G + c; if (L >= nwg) return false;
;         int wgid = (int)L; { const int q = nwg / NXCD, r = nwg % NXCD, xcd = wgid % NXCD, off = wgid / NXCD; wgid = (xcd < r ? xcd * (q + 1) : r * (q + 1) + (xcd - r) * q) + off; }
;         const int nig = WGM * nN, gid = wgid / nig, fm = gid * WGM, gsz = (nM - fm) < WGM ? (nM - fm) : WGM;
;         u.pm = fm + ((wgid % nig) % gsz); u.pn = (wgid % nig) / gsz; return true;
;     }
; template <class Epi, class Sched, bool ALIGN_EPI = false, bool SP2 = false>
; __device__ __forceinline__ void gemm_phase(PG8_LAS unsigned char* lds, const Gemm g, const Sched& S, const Epi& E) {
;     ...
;     for (;;) {
;         const bool has_next = S.next(ui + 1, nxt);
;         const char* nA = has_next ? (const char*)g.A + (size_t)nxt.pm * tstep : cA; const char* nB = has_next ? (const char*)g.Bt + (size_t)nxt.pn * tstep : cB;
;     ...
; #pragma unroll
;         for (int a = 0; a < 2; ++a)
; #pragma unroll
;             for (int b = 0; b < 2; ++b)
; #pragma unroll
;                 for (int m = 0; m < 4; ++m)
; #pragma unroll
;                     for (int n = 0; n < 2; ++n) acc[a][b][m][n] = (f32x4){0.f, 0.f, 0.f, 0.f};
;         cur = nxt; cA = nA; cB = nB; ++ui;
.LBB0_1474:
	s_mov_b32 s98, s101
	s_andn2_b64 vcc, exec, s[6:7]
	s_mov_b32 s9, s36
	s_mov_b32 s8, s38
	s_mov_b64 s[48:49], s[42:43]
	s_mov_b64 s[46:47], s[40:41]
	s_cbranch_vccz .LBB0_1484
.LBB0_1475:
	s_add_i32 s44, s44, 1
	s_mul_i32 s6, s44, s53
	s_mul_hi_u32 s7, s44, s54
	s_add_i32 s7, s7, s6
	s_mul_i32 s6, s44, s54
	s_add_u32 s40, s6, s2
	s_addc_u32 s41, s7, s14
	s_mov_b32 s101, 0
	s_cmp_eq_u32 s44, 5
	s_cbranch_scc0 .Lh7_norm
	s_and_b32 s99, s2, 0x7f
	s_add_u32 s40, s6, s99
	s_addc_u32 s41, s7, 0
	s_lshr_b32 s101, s2, 7
	s_add_i32 s101, s101, 1
.Lh7_norm:
	v_cmp_gt_i64_e32 vcc, s[40:41], v[142:143]
	v_cmp_lt_i64_e64 s[6:7], s[40:41], v[140:141]
	s_cbranch_vccnz .LBB0_1477
	s_ashr_i32 s30, s40, 31
	s_lshr_b32 s30, s30, 29
	s_add_i32 s30, s40, s30
	s_ashr_i32 s36, s30, 3
	s_and_b32 s30, s30, -8
	s_sub_i32 s30, s40, s30
	s_cmp_lt_i32 s30, 0
	s_cselect_b32 s37, s15, 0xb0
	s_mul_i32 s30, s30, s37
	s_add_i32 s30, s30, s36
	s_mul_hi_i32 s36, s30, 0x2e8ba2e9
	s_lshr_b32 s37, s36, 31
	s_ashr_i32 s36, s36, 5
	s_add_i32 s36, s36, s37
	s_lshl_b32 s37, s36, 3
	s_sub_i32 s38, 64, s37
	s_min_i32 s38, s38, 8
	s_abs_i32 s39, s38
	v_cvt_f32_u32_e32 v0, s39
	s_sub_i32 s41, 0, s39
	s_mulk_i32 s36, 0xb0
	s_sub_i32 s30, s30, s36
	v_rcp_iflag_f32_e32 v0, v0
	s_abs_i32 s36, s30
	s_xor_b32 s40, s30, s38
	s_ashr_i32 s40, s40, 31
	v_mul_f32_e32 v0, 0x4f7ffffe, v0
	v_cvt_u32_f32_e32 v0, v0
	s_nop 0
	v_readfirstlane_b32 s42, v0
	s_mul_i32 s41, s41, s42
	s_mul_hi_u32 s41, s42, s41
	s_add_i32 s42, s42, s41
	s_mul_hi_u32 s41, s36, s42
	s_mul_i32 s42, s41, s39
	s_sub_i32 s36, s36, s42
	s_add_i32 s43, s41, 1
	s_sub_i32 s42, s36, s39
	s_cmp_ge_u32 s36, s39
	s_cselect_b32 s41, s43, s41
	s_cselect_b32 s36, s42, s36
	s_add_i32 s42, s41, 1
	s_cmp_ge_u32 s36, s39
	s_cselect_b32 s36, s42, s41
	s_xor_b32 s36, s36, s40
	s_sub_i32 s36, s36, s40
	s_mul_i32 s38, s36, s38
	s_sub_i32 s30, s30, s38
	s_add_i32 s38, s37, s30
.LBB0_1477:
	s_ashr_i32 s39, s38, 31
	s_lshl_b64 s[40:41], s[38:39], 19
	s_add_u32 s40, s16, s40
	s_addc_u32 s41, s17, s41
	s_cmp_eq_u32 s101, 2
	s_cselect_b32 s99, 0x40000, 0
	s_add_u32 s40, s40, s99
	s_addc_u32 s41, s41, 0
	s_and_b64 s[42:43], s[6:7], exec
	s_cselect_b32 s39, s41, s47
	s_cselect_b32 s59, s40, s46
	s_ashr_i32 s37, s36, 31
	s_lshl_b64 s[42:43], s[36:37], 19
	v_readlane_b32 s50, v251, 48
	v_readlane_b32 s51, v251, 49
	s_add_u32 s42, s50, s42
	s_addc_u32 s43, s51, s43
	s_and_b64 s[50:51], s[6:7], exec
	s_cselect_b32 s37, s43, s49
	s_cselect_b32 s60, s42, s48
	s_add_u32 s46, s46, 0x40080
	s_addc_u32 s47, s47, 0
	s_add_u32 s61, s48, 0x100
	v_mov_b32_e32 v0, 0
	s_addc_u32 s62, s49, 0
	s_mov_b32 s63, -2
	v_mov_b32_e32 v1, v0
	v_mov_b32_e32 v2, v0
	v_mov_b32_e32 v3, v0
	v_mov_b32_e32 v4, v0
	v_mov_b32_e32 v5, v0
	v_mov_b32_e32 v6, v0
	v_mov_b32_e32 v7, v0
	v_mov_b32_e32 v16, v0
	v_mov_b32_e32 v17, v0
	v_mov_b32_e32 v18, v0
	v_mov_b32_e32 v19, v0
	v_mov_b32_e32 v20, v0
	v_mov_b32_e32 v21, v0
	v_mov_b32_e32 v22, v0
	v_mov_b32_e32 v23, v0
	v_mov_b32_e32 v32, v0
	v_mov_b32_e32 v33, v0
	v_mov_b32_e32 v34, v0
	v_mov_b32_e32 v35, v0
	v_mov_b32_e32 v36, v0
	v_mov_b32_e32 v37, v0
	v_mov_b32_e32 v38, v0
	v_mov_b32_e32 v39, v0
	v_mov_b32_e32 v48, v0
	v_mov_b32_e32 v49, v0
	v_mov_b32_e32 v50, v0
	v_mov_b32_e32 v51, v0
	v_mov_b32_e32 v52, v0
	v_mov_b32_e32 v53, v0
	v_mov_b32_e32 v54, v0
	v_mov_b32_e32 v55, v0
	v_mov_b32_e32 v8, v0
	v_mov_b32_e32 v9, v0
	v_mov_b32_e32 v10, v0
	v_mov_b32_e32 v11, v0
	v_mov_b32_e32 v12, v0
	v_mov_b32_e32 v13, v0
	v_mov_b32_e32 v14, v0
	v_mov_b32_e32 v15, v0
	v_mov_b32_e32 v24, v0
	v_mov_b32_e32 v25, v0
	v_mov_b32_e32 v26, v0
	v_mov_b32_e32 v27, v0
	v_mov_b32_e32 v28, v0
	v_mov_b32_e32 v29, v0
	v_mov_b32_e32 v30, v0
	v_mov_b32_e32 v31, v0
	v_mov_b32_e32 v40, v0
	v_mov_b32_e32 v41, v0
	v_mov_b32_e32 v42, v0
	v_mov_b32_e32 v43, v0
	v_mov_b32_e32 v44, v0
	v_mov_b32_e32 v45, v0
	v_mov_b32_e32 v46, v0
	v_mov_b32_e32 v47, v0
	v_mov_b32_e32 v56, v0
	v_mov_b32_e32 v57, v0
	v_mov_b32_e32 v58, v0
	v_mov_b32_e32 v59, v0
	v_mov_b32_e32 v60, v0
	v_mov_b32_e32 v61, v0
	v_mov_b32_e32 v62, v0
	v_mov_b32_e32 v63, v0
	v_mov_b32_e32 v64, v0
	v_mov_b32_e32 v65, v0
	v_mov_b32_e32 v66, v0
	v_mov_b32_e32 v67, v0
	v_mov_b32_e32 v68, v0
	v_mov_b32_e32 v69, v0
	v_mov_b32_e32 v70, v0
	v_mov_b32_e32 v71, v0
	v_mov_b32_e32 v80, v0
	v_mov_b32_e32 v81, v0
	v_mov_b32_e32 v82, v0
	v_mov_b32_e32 v83, v0
	v_mov_b32_e32 v84, v0
	v_mov_b32_e32 v85, v0
	v_mov_b32_e32 v86, v0
	v_mov_b32_e32 v87, v0
	v_mov_b32_e32 v96, v0
	v_mov_b32_e32 v97, v0
	v_mov_b32_e32 v98, v0
	v_mov_b32_e32 v99, v0
	v_mov_b32_e32 v100, v0
	v_mov_b32_e32 v101, v0
	v_mov_b32_e32 v102, v0
	v_mov_b32_e32 v103, v0
	v_mov_b32_e32 v112, v0
	v_mov_b32_e32 v113, v0
	v_mov_b32_e32 v114, v0
	v_mov_b32_e32 v115, v0
	v_mov_b32_e32 v116, v0
	v_mov_b32_e32 v117, v0
	v_mov_b32_e32 v118, v0
	v_mov_b32_e32 v119, v0
	v_mov_b32_e32 v72, v0
	v_mov_b32_e32 v73, v0
	v_mov_b32_e32 v74, v0
	v_mov_b32_e32 v75, v0
	v_mov_b32_e32 v76, v0
	v_mov_b32_e32 v77, v0
	v_mov_b32_e32 v78, v0
	v_mov_b32_e32 v79, v0
	v_mov_b32_e32 v88, v0
	v_mov_b32_e32 v89, v0
	v_mov_b32_e32 v90, v0
	v_mov_b32_e32 v91, v0
	v_mov_b32_e32 v92, v0
	v_mov_b32_e32 v93, v0
	v_mov_b32_e32 v94, v0
	v_mov_b32_e32 v95, v0
	v_mov_b32_e32 v104, v0
	v_mov_b32_e32 v105, v0
	v_mov_b32_e32 v106, v0
	v_mov_b32_e32 v107, v0
	v_mov_b32_e32 v108, v0
	v_mov_b32_e32 v109, v0
	v_mov_b32_e32 v110, v0
	v_mov_b32_e32 v111, v0
	v_mov_b32_e32 v120, v0
	v_mov_b32_e32 v121, v0
	v_mov_b32_e32 v122, v0
	v_mov_b32_e32 v123, v0
	v_mov_b32_e32 v124, v0
	v_mov_b32_e32 v125, v0
	v_mov_b32_e32 v126, v0
	v_mov_b32_e32 v127, v0
; #define PG8_STAGE(bufoff, gbase, voff) do { _Pragma("unroll") for (int _i = 0; _i < 2; ++_i) \
;         __builtin_amdgcn_global_load_lds((const unsigned*)((const char*)(gbase) + (voff)[_i]), (PG8_LAS unsigned*)(lds + (bufoff) + ldsw + _i * 8192), 16, 0, 0); } while (0)
; #define PG8_LDA(dst, b, h) do { _Pragma("unroll") for (int m = 0; m < 4; ++m) _Pragma("unroll") for (int k = 0; k < 2; ++k) dst[m][k] = *(const PG8_LAS bf16x8*)(lds + PG8_SA(b, h) + aoff + m * 2048 + k * 1024); } while (0)
; #define PG8_LDB(dst, b, h) do { _Pragma("unroll") for (int n = 0; n < 2; ++n) _Pragma("unroll") for (int k = 0; k < 2; ++k) dst[n][k] = *(const PG8_LAS bf16x8*)(lds + PG8_SB(b, h) + boff + n * 2048 + k * 1024); } while (0)
; #define PG8_MMA(ai, bj, At, Bt) do { __builtin_amdgcn_s_setprio(1); _Pragma("unroll") for (int m = 0; m < 4; ++m) _Pragma("unroll") for (int n = 0; n < 2; ++n) _Pragma("unroll") for (int k = 0; k < 2; ++k) \
;         acc[ai][bj][m][n] = __builtin_amdgcn_mfma_f32_16x16x32_bf16(Bt[n][k], At[m][k], acc[ai][bj][m][n], 0, 0, 0); __builtin_amdgcn_s_setprio(0); } while (0)
; #define PG8_WAIT_V(n) asm volatile("s_waitcnt vmcnt(" #n ")" ::: "memory")
; #define PG8_BAR __builtin_amdgcn_s_barrier()
; template <class Epi, class Sched, bool ALIGN_EPI = false, bool SP2 = false>
; __device__ __forceinline__ void gemm_phase(PG8_LAS unsigned char* lds, const Gemm g, const Sched& S, const Epi& E) {
;     ...
;         for (int t = 0; t < nt; t += 2) {
;             const bool last = (t == nt - 2);
;             const char* a1 = cA + (size_t)(t + 1) * kstep;
;             const char* a2 = last ? nA : cA + (size_t)(t + 2) * kstep; const char* b2 = last ? nB : cB + (size_t)(t + 2) * kstep;
;             const char* a3 = a2 + kstep; const char* b3 = b2 + kstep;
;             if (last && has_next) S.a_ready(nxt);
;             if constexpr (SP2) {
;             PG8_LDB(B0, 0, 0); PG8_LDB(B1, 0, 1); PG8_SCHED; PG8_LDA(At, 0, 0); PG8_STAGE(PG8_SA(1, 1), a1 + hstep, voffA);
;             PG8_WAIT_V(8); PG8_WAIT_L(0); PG8_BAR; PG8_MMA(0, 0, At, B0); PG8_MMA(0, 1, At, B1); PG8_BAR; PG8_SCHED;
;             PG8_LDA(At, 0, 1); PG8_STAGE(PG8_SB(0, 0), b2, voffB); PG8_STAGE(PG8_SB(0, 1), b2 + hstep, voffB); PG8_STAGE(PG8_SA(0, 0), a2, voffA);
;             PG8_WAIT_V(8); PG8_WAIT_L(0); PG8_BAR; PG8_MMA(1, 0, At, B0); PG8_MMA(1, 1, At, B1); PG8_BAR; PG8_SCHED;
.LBB0_1478:
	ds_read_b128 v[144:147], v153
	ds_read_b128 v[162:165], v153 offset:1024
	ds_read_b128 v[166:169], v153 offset:2048
	ds_read_b128 v[170:173], v153 offset:3072
	ds_read_b128 v[174:177], v159
	ds_read_b128 v[178:181], v159 offset:1024
	ds_read_b128 v[182:185], v159 offset:2048
	ds_read_b128 v[188:191], v159 offset:3072
	s_add_u32 s30, s46, 0xfffc0080
	s_addc_u32 s48, s47, -1
	s_cmp_eq_u32 s63, 12
	s_cselect_b32 s51, s39, s48
	s_cselect_b32 s50, s59, s30
	s_cselect_b32 s49, s37, s62
	s_cselect_b32 s48, s60, s61
	v_lshl_add_u64 v[148:149], s[46:47], 0, v[136:137]
	s_add_i32 m0, s31, 0xc000
	ds_read_b128 v[192:195], v160
	ds_read_b128 v[196:199], v160 offset:1024
	ds_read_b128 v[200:203], v160 offset:2048
	ds_read_b128 v[204:207], v160 offset:3072
	ds_read_b128 v[208:211], v160 offset:4096
	ds_read_b128 v[212:215], v160 offset:5120
	ds_read_b128 v[216:219], v160 offset:6144
	ds_read_b128 v[220:223], v160 offset:7168
	global_load_lds_dwordx4 v[148:149], off
	v_lshl_add_u64 v[148:149], s[46:47], 0, v[138:139]
	s_add_i32 m0, s31, 0xe000
	s_nop 0
	global_load_lds_dwordx4 v[148:149], off
	s_waitcnt vmcnt(8)
	s_waitcnt lgkmcnt(0)
	s_barrier
	s_setprio 1
	s_waitcnt lgkmcnt(0)
	v_mfma_f32_16x16x32_bf16 v[124:127], v[144:147], v[192:195], v[124:127]
	v_mfma_f32_16x16x32_bf16 v[120:123], v[166:169], v[192:195], v[120:123]
	v_mfma_f32_16x16x32_bf16 v[108:111], v[144:147], v[200:203], v[108:111]
	v_mfma_f32_16x16x32_bf16 v[104:107], v[166:169], v[200:203], v[104:107]
	v_mfma_f32_16x16x32_bf16 v[92:95], v[144:147], v[208:211], v[92:95]
	v_mfma_f32_16x16x32_bf16 v[88:91], v[166:169], v[208:211], v[88:91]
	v_mfma_f32_16x16x32_bf16 v[76:79], v[144:147], v[216:219], v[76:79]
	v_mfma_f32_16x16x32_bf16 v[72:75], v[166:169], v[216:219], v[72:75]
	v_mfma_f32_16x16x32_bf16 v[124:127], v[162:165], v[196:199], v[124:127]
	v_mfma_f32_16x16x32_bf16 v[120:123], v[170:173], v[196:199], v[120:123]
	v_mfma_f32_16x16x32_bf16 v[108:111], v[162:165], v[204:207], v[108:111]
	v_mfma_f32_16x16x32_bf16 v[104:107], v[170:173], v[204:207], v[104:107]
	v_mfma_f32_16x16x32_bf16 v[92:95], v[162:165], v[212:215], v[92:95]
	v_mfma_f32_16x16x32_bf16 v[88:91], v[170:173], v[212:215], v[88:91]
	v_mfma_f32_16x16x32_bf16 v[76:79], v[162:165], v[220:223], v[76:79]
	v_mfma_f32_16x16x32_bf16 v[72:75], v[170:173], v[220:223], v[72:75]
	s_setprio 0
	s_setprio 1
	v_mfma_f32_16x16x32_bf16 v[116:119], v[174:177], v[192:195], v[116:119]
	v_mfma_f32_16x16x32_bf16 v[112:115], v[182:185], v[192:195], v[112:115]
	v_mfma_f32_16x16x32_bf16 v[100:103], v[174:177], v[200:203], v[100:103]
	v_mfma_f32_16x16x32_bf16 v[96:99], v[182:185], v[200:203], v[96:99]
	v_mfma_f32_16x16x32_bf16 v[84:87], v[174:177], v[208:211], v[84:87]
	v_mfma_f32_16x16x32_bf16 v[80:83], v[182:185], v[208:211], v[80:83]
	v_mfma_f32_16x16x32_bf16 v[68:71], v[174:177], v[216:219], v[68:71]
	v_mfma_f32_16x16x32_bf16 v[64:67], v[182:185], v[216:219], v[64:67]
	v_mfma_f32_16x16x32_bf16 v[116:119], v[178:181], v[196:199], v[116:119]
	v_mfma_f32_16x16x32_bf16 v[112:115], v[188:191], v[196:199], v[112:115]
	v_mfma_f32_16x16x32_bf16 v[100:103], v[178:181], v[204:207], v[100:103]
	v_mfma_f32_16x16x32_bf16 v[96:99], v[188:191], v[204:207], v[96:99]
	v_mfma_f32_16x16x32_bf16 v[84:87], v[178:181], v[212:215], v[84:87]
	v_mfma_f32_16x16x32_bf16 v[80:83], v[188:191], v[212:215], v[80:83]
	v_mfma_f32_16x16x32_bf16 v[68:71], v[178:181], v[220:223], v[68:71]
	v_mfma_f32_16x16x32_bf16 v[64:67], v[188:191], v[220:223], v[64:67]
	s_setprio 0
	s_barrier
	s_add_i32 s30, s55, s3
	v_lshl_add_u64 v[148:149], s[48:49], 0, v[132:133]
	s_mov_b32 m0, s30
	ds_read_b128 v[192:195], v160 offset:16384
	ds_read_b128 v[196:199], v160 offset:17408
	ds_read_b128 v[200:203], v160 offset:18432
	ds_read_b128 v[204:207], v160 offset:19456
	ds_read_b128 v[208:211], v160 offset:20480
	ds_read_b128 v[212:215], v160 offset:21504
	ds_read_b128 v[216:219], v160 offset:22528
	ds_read_b128 v[220:223], v160 offset:23552
	global_load_lds_dwordx4 v[148:149], off
	s_add_i32 m0, s30, 0x2000
	s_add_u32 s64, s48, 0x40000
	v_lshl_add_u64 v[224:225], s[48:49], 0, v[128:129]
	s_addc_u32 s65, s49, 0
	s_add_i32 s30, s56, s3
	global_load_lds_dwordx4 v[224:225], off
	v_lshl_add_u64 v[226:227], s[64:65], 0, v[132:133]
	s_mov_b32 m0, s30
	v_lshl_add_u64 v[230:231], s[50:51], 0, v[130:131]
	global_load_lds_dwordx4 v[226:227], off
	v_lshl_add_u64 v[226:227], s[64:65], 0, v[128:129]
	s_add_i32 m0, s30, 0x2000
	s_nop 0
	global_load_lds_dwordx4 v[226:227], off
	v_lshl_add_u64 v[226:227], s[50:51], 0, v[134:135]
	s_mov_b32 m0, s31
	s_nop 0
	global_load_lds_dwordx4 v[226:227], off
	s_mov_b32 m0, s33
	s_nop 0
	global_load_lds_dwordx4 v[230:231], off
	s_waitcnt vmcnt(8)
	s_waitcnt lgkmcnt(0)
	s_barrier
	s_cmp_lg_u32 s98, 0
	s_cbranch_scc1 .Lh7_sk0
	s_setprio 1
	s_waitcnt lgkmcnt(0)
	v_mfma_f32_16x16x32_bf16 v[60:63], v[144:147], v[192:195], v[60:63]
	v_mfma_f32_16x16x32_bf16 v[56:59], v[166:169], v[192:195], v[56:59]
	v_mfma_f32_16x16x32_bf16 v[44:47], v[144:147], v[200:203], v[44:47]
	v_mfma_f32_16x16x32_bf16 v[40:43], v[166:169], v[200:203], v[40:43]
	v_mfma_f32_16x16x32_bf16 v[28:31], v[144:147], v[208:211], v[28:31]
	v_mfma_f32_16x16x32_bf16 v[24:27], v[166:169], v[208:211], v[24:27]
	v_mfma_f32_16x16x32_bf16 v[12:15], v[144:147], v[216:219], v[12:15]
	v_mfma_f32_16x16x32_bf16 v[8:11], v[166:169], v[216:219], v[8:11]
	v_mfma_f32_16x16x32_bf16 v[60:63], v[162:165], v[196:199], v[60:63]
	v_mfma_f32_16x16x32_bf16 v[56:59], v[170:173], v[196:199], v[56:59]
	v_mfma_f32_16x16x32_bf16 v[44:47], v[162:165], v[204:207], v[44:47]
	v_mfma_f32_16x16x32_bf16 v[40:43], v[170:173], v[204:207], v[40:43]
	v_mfma_f32_16x16x32_bf16 v[28:31], v[162:165], v[212:215], v[28:31]
	v_mfma_f32_16x16x32_bf16 v[24:27], v[170:173], v[212:215], v[24:27]
	v_mfma_f32_16x16x32_bf16 v[12:15], v[162:165], v[220:223], v[12:15]
	v_mfma_f32_16x16x32_bf16 v[8:11], v[170:173], v[220:223], v[8:11]
	s_setprio 0
	s_setprio 1
	v_mfma_f32_16x16x32_bf16 v[52:55], v[174:177], v[192:195], v[52:55]
	v_mfma_f32_16x16x32_bf16 v[48:51], v[182:185], v[192:195], v[48:51]
	v_mfma_f32_16x16x32_bf16 v[36:39], v[174:177], v[200:203], v[36:39]
	v_mfma_f32_16x16x32_bf16 v[32:35], v[182:185], v[200:203], v[32:35]
	v_mfma_f32_16x16x32_bf16 v[20:23], v[174:177], v[208:211], v[20:23]
	v_mfma_f32_16x16x32_bf16 v[16:19], v[182:185], v[208:211], v[16:19]
	v_mfma_f32_16x16x32_bf16 v[4:7], v[174:177], v[216:219], v[4:7]
	v_mfma_f32_16x16x32_bf16 v[0:3], v[182:185], v[216:219], v[0:3]
	v_mfma_f32_16x16x32_bf16 v[52:55], v[178:181], v[196:199], v[52:55]
	v_mfma_f32_16x16x32_bf16 v[48:51], v[188:191], v[196:199], v[48:51]
	v_mfma_f32_16x16x32_bf16 v[36:39], v[178:181], v[204:207], v[36:39]
	v_mfma_f32_16x16x32_bf16 v[32:35], v[188:191], v[204:207], v[32:35]
	v_mfma_f32_16x16x32_bf16 v[20:23], v[178:181], v[212:215], v[20:23]
	v_mfma_f32_16x16x32_bf16 v[16:19], v[188:191], v[212:215], v[16:19]
	v_mfma_f32_16x16x32_bf16 v[4:7], v[178:181], v[220:223], v[4:7]
	v_mfma_f32_16x16x32_bf16 v[0:3], v[188:191], v[220:223], v[0:3]
	s_setprio 0
; #define PG8_STAGE(bufoff, gbase, voff) do { _Pragma("unroll") for (int _i = 0; _i < 2; ++_i) \
;         __builtin_amdgcn_global_load_lds((const unsigned*)((const char*)(gbase) + (voff)[_i]), (PG8_LAS unsigned*)(lds + (bufoff) + ldsw + _i * 8192), 16, 0, 0); } while (0)
; #define PG8_LDA(dst, b, h) do { _Pragma("unroll") for (int m = 0; m < 4; ++m) _Pragma("unroll") for (int k = 0; k < 2; ++k) dst[m][k] = *(const PG8_LAS bf16x8*)(lds + PG8_SA(b, h) + aoff + m * 2048 + k * 1024); } while (0)
; #define PG8_LDB(dst, b, h) do { _Pragma("unroll") for (int n = 0; n < 2; ++n) _Pragma("unroll") for (int k = 0; k < 2; ++k) dst[n][k] = *(const PG8_LAS bf16x8*)(lds + PG8_SB(b, h) + boff + n * 2048 + k * 1024); } while (0)
; #define PG8_MMA(ai, bj, At, Bt) do { __builtin_amdgcn_s_setprio(1); _Pragma("unroll") for (int m = 0; m < 4; ++m) _Pragma("unroll") for (int n = 0; n < 2; ++n) _Pragma("unroll") for (int k = 0; k < 2; ++k) \
;         acc[ai][bj][m][n] = __builtin_amdgcn_mfma_f32_16x16x32_bf16(Bt[n][k], At[m][k], acc[ai][bj][m][n], 0, 0, 0); __builtin_amdgcn_s_setprio(0); } while (0)
; #define PG8_WAIT_V(n) asm volatile("s_waitcnt vmcnt(" #n ")" ::: "memory")
; #define PG8_WAIT_L(n) asm volatile("s_waitcnt lgkmcnt(" #n ")" ::: "memory")
; #define PG8_BAR __builtin_amdgcn_s_barrier()
; #define PG8_SCHED __builtin_amdgcn_sched_barrier(0)
; template <class Epi, class Sched, bool ALIGN_EPI = false, bool SP2 = false>
; __device__ __forceinline__ void gemm_phase(PG8_LAS unsigned char* lds, const Gemm g, const Sched& S, const Epi& E) {
;     ...
;             PG8_LDB(B0, 1, 0); PG8_LDB(B1, 1, 1); PG8_SCHED; PG8_LDA(At, 1, 0); PG8_STAGE(PG8_SA(0, 1), a2 + hstep, voffA);
;             PG8_WAIT_V(8); PG8_WAIT_L(0); PG8_BAR; PG8_MMA(0, 0, At, B0); PG8_MMA(0, 1, At, B1); PG8_BAR; PG8_SCHED;
;             PG8_LDA(At, 1, 1); PG8_STAGE(PG8_SB(1, 0), b3, voffB); PG8_STAGE(PG8_SB(1, 1), b3 + hstep, voffB); PG8_STAGE(PG8_SA(1, 0), a3, voffA);
;             PG8_WAIT_V(8); PG8_WAIT_L(0); PG8_BAR; PG8_MMA(1, 0, At, B0); PG8_MMA(1, 1, At, B1); PG8_BAR; PG8_SCHED;
.Lh7_sk0:
	s_barrier
	s_add_i32 s30, 0, 0x18000
	s_add_i32 s64, 0, 0x1c000
	v_add_u32_e32 v170, s30, v151
	v_add_u32_e32 v188, s64, v151
	ds_read_b128 v[144:147], v170
	ds_read_b128 v[162:165], v170 offset:1024
	ds_read_b128 v[166:169], v170 offset:2048
	ds_read_b128 v[170:173], v170 offset:3072
	ds_read_b128 v[174:177], v188
	ds_read_b128 v[178:181], v188 offset:1024
	ds_read_b128 v[182:185], v188 offset:2048
	ds_read_b128 v[188:191], v188 offset:3072
	s_add_u32 s50, s50, 0x40000
	s_addc_u32 s51, s51, 0
	s_mov_b32 m0, s34
	v_lshl_add_u64 v[232:233], s[50:51], 0, v[134:135]
	ds_read_b128 v[192:195], v160 offset:32768
	ds_read_b128 v[196:199], v160 offset:33792
	ds_read_b128 v[200:203], v160 offset:34816
	ds_read_b128 v[204:207], v160 offset:35840
	ds_read_b128 v[208:211], v160 offset:36864
	ds_read_b128 v[212:215], v160 offset:37888
	ds_read_b128 v[216:219], v160 offset:38912
	ds_read_b128 v[220:223], v160 offset:39936
	global_load_lds_dwordx4 v[232:233], off
	v_lshl_add_u64 v[232:233], s[50:51], 0, v[130:131]
	s_mov_b32 m0, s35
	s_nop 0
	global_load_lds_dwordx4 v[232:233], off
	s_waitcnt vmcnt(8)
	s_waitcnt lgkmcnt(0)
	s_barrier
	s_setprio 1
	s_waitcnt lgkmcnt(0)
	v_mfma_f32_16x16x32_bf16 v[124:127], v[144:147], v[192:195], v[124:127]
	v_mfma_f32_16x16x32_bf16 v[120:123], v[166:169], v[192:195], v[120:123]
	v_mfma_f32_16x16x32_bf16 v[108:111], v[144:147], v[200:203], v[108:111]
	v_mfma_f32_16x16x32_bf16 v[104:107], v[166:169], v[200:203], v[104:107]
	v_mfma_f32_16x16x32_bf16 v[92:95], v[144:147], v[208:211], v[92:95]
	v_mfma_f32_16x16x32_bf16 v[88:91], v[166:169], v[208:211], v[88:91]
	v_mfma_f32_16x16x32_bf16 v[76:79], v[144:147], v[216:219], v[76:79]
	v_mfma_f32_16x16x32_bf16 v[72:75], v[166:169], v[216:219], v[72:75]
	v_mfma_f32_16x16x32_bf16 v[124:127], v[162:165], v[196:199], v[124:127]
	v_mfma_f32_16x16x32_bf16 v[120:123], v[170:173], v[196:199], v[120:123]
	v_mfma_f32_16x16x32_bf16 v[108:111], v[162:165], v[204:207], v[108:111]
	v_mfma_f32_16x16x32_bf16 v[104:107], v[170:173], v[204:207], v[104:107]
	v_mfma_f32_16x16x32_bf16 v[92:95], v[162:165], v[212:215], v[92:95]
	v_mfma_f32_16x16x32_bf16 v[88:91], v[170:173], v[212:215], v[88:91]
	v_mfma_f32_16x16x32_bf16 v[76:79], v[162:165], v[220:223], v[76:79]
	v_mfma_f32_16x16x32_bf16 v[72:75], v[170:173], v[220:223], v[72:75]
	s_setprio 0
	s_setprio 1
	v_mfma_f32_16x16x32_bf16 v[116:119], v[174:177], v[192:195], v[116:119]
	v_mfma_f32_16x16x32_bf16 v[112:115], v[182:185], v[192:195], v[112:115]
	v_mfma_f32_16x16x32_bf16 v[100:103], v[174:177], v[200:203], v[100:103]
	v_mfma_f32_16x16x32_bf16 v[96:99], v[182:185], v[200:203], v[96:99]
	v_mfma_f32_16x16x32_bf16 v[84:87], v[174:177], v[208:211], v[84:87]
	v_mfma_f32_16x16x32_bf16 v[80:83], v[182:185], v[208:211], v[80:83]
	v_mfma_f32_16x16x32_bf16 v[68:71], v[174:177], v[216:219], v[68:71]
	v_mfma_f32_16x16x32_bf16 v[64:67], v[182:185], v[216:219], v[64:67]
	v_mfma_f32_16x16x32_bf16 v[116:119], v[178:181], v[196:199], v[116:119]
	v_mfma_f32_16x16x32_bf16 v[112:115], v[188:191], v[196:199], v[112:115]
	v_mfma_f32_16x16x32_bf16 v[100:103], v[178:181], v[204:207], v[100:103]
	v_mfma_f32_16x16x32_bf16 v[96:99], v[188:191], v[204:207], v[96:99]
	v_mfma_f32_16x16x32_bf16 v[84:87], v[178:181], v[212:215], v[84:87]
	v_mfma_f32_16x16x32_bf16 v[80:83], v[188:191], v[212:215], v[80:83]
	v_mfma_f32_16x16x32_bf16 v[68:71], v[178:181], v[220:223], v[68:71]
	v_mfma_f32_16x16x32_bf16 v[64:67], v[188:191], v[220:223], v[64:67]
	s_setprio 0
	s_barrier
	s_add_i32 s30, s30, s3
	v_lshl_add_u64 v[148:149], v[148:149], 0, s[12:13]
	s_mov_b32 m0, s30
	ds_read_b128 v[192:195], v160 offset:49152
	ds_read_b128 v[196:199], v160 offset:50176
	ds_read_b128 v[200:203], v160 offset:51200
	ds_read_b128 v[204:207], v160 offset:52224
	ds_read_b128 v[208:211], v160 offset:53248
	ds_read_b128 v[212:215], v160 offset:54272
	ds_read_b128 v[216:219], v160 offset:55296
	ds_read_b128 v[220:223], v160 offset:56320
	global_load_lds_dwordx4 v[148:149], off
	s_add_i32 m0, s30, 0x2000
	s_add_u32 s48, s48, 0x40080
	v_lshl_add_u64 v[148:149], v[224:225], 0, s[12:13]
	s_addc_u32 s49, s49, 0
	s_add_i32 s30, s64, s3
	global_load_lds_dwordx4 v[148:149], off
	v_lshl_add_u64 v[148:149], s[48:49], 0, v[132:133]
	s_mov_b32 m0, s30
	s_nop 0
	global_load_lds_dwordx4 v[148:149], off
	v_lshl_add_u64 v[148:149], s[48:49], 0, v[128:129]
	s_add_i32 m0, s30, 0x2000
	s_nop 0
	global_load_lds_dwordx4 v[148:149], off
	v_lshl_add_u64 v[148:149], v[226:227], 0, s[12:13]
	s_mov_b32 m0, s45
	s_nop 0
	global_load_lds_dwordx4 v[148:149], off
	v_lshl_add_u64 v[148:149], v[230:231], 0, s[12:13]
	s_mov_b32 m0, s52
	s_nop 0
	global_load_lds_dwordx4 v[148:149], off
	s_waitcnt vmcnt(8)
	s_waitcnt lgkmcnt(0)
	s_barrier
	s_cmp_lg_u32 s98, 0
	s_cbranch_scc1 .Lh7_sk1
	s_setprio 1
	s_waitcnt lgkmcnt(0)
	v_mfma_f32_16x16x32_bf16 v[60:63], v[144:147], v[192:195], v[60:63]
	v_mfma_f32_16x16x32_bf16 v[56:59], v[166:169], v[192:195], v[56:59]
	v_mfma_f32_16x16x32_bf16 v[44:47], v[144:147], v[200:203], v[44:47]
	v_mfma_f32_16x16x32_bf16 v[40:43], v[166:169], v[200:203], v[40:43]
	v_mfma_f32_16x16x32_bf16 v[28:31], v[144:147], v[208:211], v[28:31]
	v_mfma_f32_16x16x32_bf16 v[24:27], v[166:169], v[208:211], v[24:27]
	v_mfma_f32_16x16x32_bf16 v[12:15], v[144:147], v[216:219], v[12:15]
	v_mfma_f32_16x16x32_bf16 v[8:11], v[166:169], v[216:219], v[8:11]
	v_mfma_f32_16x16x32_bf16 v[60:63], v[162:165], v[196:199], v[60:63]
	v_mfma_f32_16x16x32_bf16 v[56:59], v[170:173], v[196:199], v[56:59]
	v_mfma_f32_16x16x32_bf16 v[44:47], v[162:165], v[204:207], v[44:47]
	v_mfma_f32_16x16x32_bf16 v[40:43], v[170:173], v[204:207], v[40:43]
	v_mfma_f32_16x16x32_bf16 v[28:31], v[162:165], v[212:215], v[28:31]
	v_mfma_f32_16x16x32_bf16 v[24:27], v[170:173], v[212:215], v[24:27]
	v_mfma_f32_16x16x32_bf16 v[12:15], v[162:165], v[220:223], v[12:15]
	v_mfma_f32_16x16x32_bf16 v[8:11], v[170:173], v[220:223], v[8:11]
	s_setprio 0
	s_setprio 1
	v_mfma_f32_16x16x32_bf16 v[52:55], v[174:177], v[192:195], v[52:55]
	v_mfma_f32_16x16x32_bf16 v[48:51], v[182:185], v[192:195], v[48:51]
	v_mfma_f32_16x16x32_bf16 v[36:39], v[174:177], v[200:203], v[36:39]
	v_mfma_f32_16x16x32_bf16 v[32:35], v[182:185], v[200:203], v[32:35]
	v_mfma_f32_16x16x32_bf16 v[20:23], v[174:177], v[208:211], v[20:23]
	v_mfma_f32_16x16x32_bf16 v[16:19], v[182:185], v[208:211], v[16:19]
	v_mfma_f32_16x16x32_bf16 v[4:7], v[174:177], v[216:219], v[4:7]
	v_mfma_f32_16x16x32_bf16 v[0:3], v[182:185], v[216:219], v[0:3]
	v_mfma_f32_16x16x32_bf16 v[52:55], v[178:181], v[196:199], v[52:55]
	v_mfma_f32_16x16x32_bf16 v[48:51], v[188:191], v[196:199], v[48:51]
	v_mfma_f32_16x16x32_bf16 v[36:39], v[178:181], v[204:207], v[36:39]
	v_mfma_f32_16x16x32_bf16 v[32:35], v[188:191], v[204:207], v[32:35]
	v_mfma_f32_16x16x32_bf16 v[20:23], v[178:181], v[212:215], v[20:23]
	v_mfma_f32_16x16x32_bf16 v[16:19], v[188:191], v[212:215], v[16:19]
	v_mfma_f32_16x16x32_bf16 v[4:7], v[178:181], v[220:223], v[4:7]
	v_mfma_f32_16x16x32_bf16 v[0:3], v[188:191], v[220:223], v[0:3]
	s_setprio 0
; #define PG8_BAR __builtin_amdgcn_s_barrier()
; __device__ __forceinline__ float sigmoidf_(float v) { return __builtin_amdgcn_rcpf(1.f + __builtin_amdgcn_exp2f(-v * LOG2E)); }
; __device__ __forceinline__ v4u pack8(f32x4 a, f32x4 b) { v4u r; r.x = cvt_pk_bf16(a[0], a[1]); r.y = cvt_pk_bf16(a[2], a[3]); r.z = cvt_pk_bf16(b[0], b[1]); r.w = cvt_pk_bf16(b[2], b[3]); return r; }
; template <class Epi, class Sched, bool ALIGN_EPI = false, bool SP2 = false>
; __device__ __forceinline__ void gemm_phase(PG8_LAS unsigned char* lds, const Gemm g, const Sched& S, const Epi& E) {
;     ...
;         }
;         if constexpr (ALIGN_EPI) { if (wr == 0) PG8_BAR; }
;     __device__ __forceinline__ void operator()(const f32x4 (&acc)[2][2][4][2], const Unit& u, int wr, int wc, int fr, int fq) const {
;         const int row0 = u.pm * 256 + wr * 64 + fr, col0 = u.pn * 128 + wc * 32 + 8 * fq;
; #pragma unroll
;         for (int ai = 0; ai < 2; ++ai)
; #pragma unroll
;             for (int m = 0; m < 4; ++m) {
;                 const int row = row0 + ai * 128 + m * 16;
;                 float sq = 0.f;
; #pragma unroll
;                 for (int k = 0; k < 4; ++k) { const f32x4 p = *(const f32x4*)(ss1 + (size_t)row * 16 + 4 * k); sq += (p[0] + p[1]) + (p[2] + p[3]); }
;                 const float rs = rsqrtf(sq * (1.f / 1024.f) + EPS);
;                 f32x4 o[2];
; #pragma unroll
;                 for (int n = 0; n < 2; ++n) {
;                     const f32x4 g = acc[ai][0][m][n] * rs, up = acc[ai][1][m][n] * rs;
; #pragma unroll
;                     for (int j = 0; j < 4; ++j) o[n][j] = g[j] * sigmoidf_(g[j]) * up[j];
;                 }
;                 *(v4u*)(H + (size_t)row * FF + col0) = pack8(o[0], o[1]);
;             }
.Lh7_sk1:
	s_barrier
	s_add_i32 s63, s63, 2
	s_add_u32 s46, s46, 0x100
	s_addc_u32 s47, s47, 0
	s_add_u32 s61, s61, 0x100
	s_addc_u32 s62, s62, 0
	s_cmp_gt_u32 s63, 13
	s_cbranch_scc0 .LBB0_1478
	s_and_b64 vcc, exec, s[20:21]
	s_cbranch_vccz .LBB0_1481
	s_barrier
.LBB0_1481:
	v_lshl_add_u32 v148, s8, 8, v150
	s_cmp_eq_u32 s98, 2
	s_cselect_b32 s99, 0x80, 0
	v_add_u32_e32 v148, s99, v148
	v_ashrrev_i32_e32 v149, 31, v148
	v_lshlrev_b64 v[144:145], 6, v[148:149]
	v_lshl_add_u64 v[144:145], s[18:19], 0, v[144:145]
	global_load_dwordx4 v[162:165], v[144:145], off
	global_load_dwordx4 v[166:169], v[144:145], off offset:16
	global_load_dwordx4 v[170:173], v[144:145], off offset:32
	global_load_dwordx4 v[174:177], v[144:145], off offset:48
	v_lshl_or_b32 v146, s9, 7, v152
	v_mov_b64_e32 v[144:145], s[28:29]
	v_ashrrev_i32_e32 v147, 31, v146
	v_mad_i64_i32 v[178:179], s[8:9], v148, s58, v[144:145]
	v_lshlrev_b64 v[146:147], 1, v[146:147]
	v_or_b32_e32 v180, 16, v148
	v_ashrrev_i32_e32 v181, 31, v180
	s_waitcnt vmcnt(0)
	v_mov_b32_e32 v182, v163
	v_mov_b32_e32 v183, v164
	v_mov_b32_e32 v163, v165
	v_mov_b32_e32 v164, v167
	v_mov_b32_e32 v165, v168
	v_mov_b32_e32 v167, v169
	v_pk_add_f32 v[162:163], v[182:183], v[162:163]
	v_pk_add_f32 v[164:165], v[164:165], v[166:167]
	v_add_f32_e32 v149, v162, v163
	v_pk_add_f32 v[162:163], v[164:165], v[164:165] op_sel:[0,1] op_sel_hi:[1,0]
	v_add_f32_e32 v168, v170, v171
	v_add_f32_e32 v170, v172, v173
	v_mov_b32_e32 v173, v174
	v_mov_b32_e32 v169, v176
	v_mov_b32_e32 v171, v177
	v_add_f32_e32 v172, 0, v149
	v_mov_b32_e32 v163, v175
	v_pk_add_f32 v[166:167], v[168:169], v[170:171]
	v_pk_add_f32 v[162:163], v[172:173], v[162:163]
	v_lshlrev_b64 v[164:165], 6, v[180:181]
	v_pk_add_f32 v[162:163], v[162:163], v[166:167]
	v_lshl_add_u64 v[164:165], s[18:19], 0, v[164:165]
	v_add_f32_e32 v149, v162, v163
	v_fmamk_f32 v149, v149, 0x3a800000, v161
	v_mul_f32_e32 v162, 0x4b800000, v149
	v_cmp_gt_f32_e32 vcc, s57, v149
	s_nop 1
	v_cndmask_b32_e32 v149, v149, v162, vcc
	v_rsq_f32_e32 v149, v149
	v_lshl_add_u64 v[162:163], v[178:179], 0, v[146:147]
	v_mul_f32_e32 v166, 0x45800000, v149
	v_cndmask_b32_e32 v166, v149, v166, vcc
	v_pk_mul_f32 v[124:125], v[124:125], v[166:167] op_sel_hi:[1,0]
	v_pk_mul_f32 v[126:127], v[126:127], v[166:167] op_sel_hi:[1,0]
	v_pk_mul_f32 v[120:121], v[120:121], v[166:167] op_sel_hi:[1,0]
	v_pk_mul_f32 v[122:123], v[122:123], v[166:167] op_sel_hi:[1,0]
	v_pk_mul_f32 v[116:117], v[116:117], v[166:167] op_sel_hi:[1,0]
	v_pk_mul_f32 v[118:119], v[118:119], v[166:167] op_sel_hi:[1,0]
	v_pk_mul_f32 v[112:113], v[112:113], v[166:167] op_sel_hi:[1,0]
	v_pk_mul_f32 v[114:115], v[114:115], v[166:167] op_sel_hi:[1,0]
	v_mul_f32_e32 v149, 0xbfb8aa3b, v124
	v_mul_f32_e32 v166, 0xbfb8aa3b, v125
	v_mul_f32_e32 v167, 0xbfb8aa3b, v126
	v_mul_f32_e32 v168, 0xbfb8aa3b, v127
	v_mul_f32_e32 v169, 0xbfb8aa3b, v120
	v_mul_f32_e32 v170, 0xbfb8aa3b, v121
	v_mul_f32_e32 v171, 0xbfb8aa3b, v122
	v_mul_f32_e32 v172, 0xbfb8aa3b, v123
	v_exp_f32_e32 v149, v149
	v_exp_f32_e32 v166, v166
	v_exp_f32_e32 v167, v167
	v_exp_f32_e32 v168, v168
	v_exp_f32_e32 v169, v169
	v_exp_f32_e32 v170, v170
	v_exp_f32_e32 v171, v171
	v_exp_f32_e32 v172, v172
	v_add_f32_e32 v149, 1.0, v149
	v_add_f32_e32 v173, 1.0, v166
	v_add_f32_e32 v174, 1.0, v167
	v_add_f32_e32 v175, 1.0, v168
	v_add_f32_e32 v176, 1.0, v169
	v_add_f32_e32 v177, 1.0, v170
	v_add_f32_e32 v178, 1.0, v171
	v_add_f32_e32 v179, 1.0, v172
	v_rcp_f32_e32 v166, v149
	v_rcp_f32_e32 v167, v173
	v_rcp_f32_e32 v168, v174
	v_rcp_f32_e32 v169, v175
	v_rcp_f32_e32 v170, v176
	v_rcp_f32_e32 v171, v177
	v_rcp_f32_e32 v172, v178
	v_rcp_f32_e32 v173, v179
	v_pk_mul_f32 v[124:125], v[124:125], v[166:167]
	v_pk_mul_f32 v[126:127], v[126:127], v[168:169]
	v_pk_mul_f32 v[120:121], v[120:121], v[170:171]
	v_pk_mul_f32 v[122:123], v[122:123], v[172:173]
	v_pk_mul_f32 v[116:117], v[116:117], v[124:125]
	v_pk_mul_f32 v[118:119], v[118:119], v[126:127]
	v_pk_mul_f32 v[120:121], v[112:113], v[120:121]
	v_pk_mul_f32 v[122:123], v[114:115], v[122:123]
	v_cvt_pk_bf16_f32 v112, v116, v117
	v_cvt_pk_bf16_f32 v113, v118, v119
	v_cvt_pk_bf16_f32 v114, v120, v121
	v_cvt_pk_bf16_f32 v115, v122, v123
	global_store_dwordx4 v[162:163], v[112:115], off
	global_load_dwordx4 v[112:115], v[164:165], off
	s_nop 0
	global_load_dwordx4 v[116:119], v[164:165], off offset:16
	global_load_dwordx4 v[120:123], v[164:165], off offset:32
	global_load_dwordx4 v[124:127], v[164:165], off offset:48
	v_or_b32_e32 v162, 32, v148
	v_mad_i64_i32 v[164:165], s[8:9], v180, s58, v[144:145]
	v_ashrrev_i32_e32 v163, 31, v162
	s_waitcnt vmcnt(3)
	v_mov_b32_e32 v166, v113
	v_mov_b32_e32 v167, v114
	v_mov_b32_e32 v113, v115
	s_waitcnt vmcnt(2)
	v_mov_b32_e32 v114, v117
	v_mov_b32_e32 v115, v118
	v_mov_b32_e32 v117, v119
	s_waitcnt vmcnt(1)
	v_add_f32_e32 v118, v120, v121
	v_add_f32_e32 v120, v122, v123
	s_waitcnt vmcnt(0)
; __device__ __forceinline__ float sigmoidf_(float v) { return __builtin_amdgcn_rcpf(1.f + __builtin_amdgcn_exp2f(-v * LOG2E)); }
; __device__ __forceinline__ v4u pack8(f32x4 a, f32x4 b) { v4u r; r.x = cvt_pk_bf16(a[0], a[1]); r.y = cvt_pk_bf16(a[2], a[3]); r.z = cvt_pk_bf16(b[0], b[1]); r.w = cvt_pk_bf16(b[2], b[3]); return r; }
;     __device__ __forceinline__ void operator()(const f32x4 (&acc)[2][2][4][2], const Unit& u, int wr, int wc, int fr, int fq) const {
;     ...
;         for (int ai = 0; ai < 2; ++ai)
; #pragma unroll
;             for (int m = 0; m < 4; ++m) {
;                 const int row = row0 + ai * 128 + m * 16;
;                 float sq = 0.f;
; #pragma unroll
;                 for (int k = 0; k < 4; ++k) { const f32x4 p = *(const f32x4*)(ss1 + (size_t)row * 16 + 4 * k); sq += (p[0] + p[1]) + (p[2] + p[3]); }
;                 const float rs = rsqrtf(sq * (1.f / 1024.f) + EPS);
;                 f32x4 o[2];
; #pragma unroll
;                 for (int n = 0; n < 2; ++n) {
;                     const f32x4 g = acc[ai][0][m][n] * rs, up = acc[ai][1][m][n] * rs;
; #pragma unroll
;                     for (int j = 0; j < 4; ++j) o[n][j] = g[j] * sigmoidf_(g[j]) * up[j];
;                 }
;                 *(v4u*)(H + (size_t)row * FF + col0) = pack8(o[0], o[1]);
;             }
	v_mov_b32_e32 v119, v126
	v_mov_b32_e32 v121, v127
	v_pk_add_f32 v[112:113], v[166:167], v[112:113]
	v_pk_add_f32 v[114:115], v[114:115], v[116:117]
	v_pk_add_f32 v[116:117], v[118:119], v[120:121]
	v_add_f32_e32 v118, v112, v113
	v_pk_add_f32 v[112:113], v[114:115], v[114:115] op_sel:[0,1] op_sel_hi:[1,0]
	v_mov_b32_e32 v123, v124
	v_add_f32_e32 v122, 0, v118
	v_mov_b32_e32 v113, v125
	v_pk_add_f32 v[112:113], v[122:123], v[112:113]
	v_lshlrev_b64 v[114:115], 6, v[162:163]
	v_pk_add_f32 v[112:113], v[112:113], v[116:117]
	v_lshl_add_u64 v[114:115], s[18:19], 0, v[114:115]
	v_add_f32_e32 v112, v112, v113
	v_fmamk_f32 v112, v112, 0x3a800000, v161
	v_mul_f32_e32 v113, 0x4b800000, v112
	v_cmp_gt_f32_e32 vcc, s57, v112
	s_nop 1
	v_cndmask_b32_e32 v112, v112, v113, vcc
	v_rsq_f32_e32 v116, v112
	v_lshl_add_u64 v[112:113], v[164:165], 0, v[146:147]
	v_mul_f32_e32 v117, 0x45800000, v116
	v_cndmask_b32_e32 v116, v116, v117, vcc
	v_pk_mul_f32 v[108:109], v[108:109], v[116:117] op_sel_hi:[1,0]
	v_pk_mul_f32 v[110:111], v[110:111], v[116:117] op_sel_hi:[1,0]
	v_pk_mul_f32 v[104:105], v[104:105], v[116:117] op_sel_hi:[1,0]
	v_pk_mul_f32 v[106:107], v[106:107], v[116:117] op_sel_hi:[1,0]
	v_pk_mul_f32 v[100:101], v[100:101], v[116:117] op_sel_hi:[1,0]
	v_pk_mul_f32 v[102:103], v[102:103], v[116:117] op_sel_hi:[1,0]
	v_pk_mul_f32 v[96:97], v[96:97], v[116:117] op_sel_hi:[1,0]
	v_pk_mul_f32 v[98:99], v[98:99], v[116:117] op_sel_hi:[1,0]
	v_mul_f32_e32 v116, 0xbfb8aa3b, v108
	v_mul_f32_e32 v117, 0xbfb8aa3b, v109
	v_mul_f32_e32 v118, 0xbfb8aa3b, v110
	v_mul_f32_e32 v119, 0xbfb8aa3b, v111
	v_mul_f32_e32 v120, 0xbfb8aa3b, v104
	v_mul_f32_e32 v121, 0xbfb8aa3b, v105
	v_mul_f32_e32 v122, 0xbfb8aa3b, v106
	v_mul_f32_e32 v123, 0xbfb8aa3b, v107
	v_exp_f32_e32 v116, v116
	v_exp_f32_e32 v117, v117
	v_exp_f32_e32 v118, v118
	v_exp_f32_e32 v119, v119
	v_exp_f32_e32 v120, v120
	v_exp_f32_e32 v121, v121
	v_exp_f32_e32 v122, v122
	v_exp_f32_e32 v123, v123
	v_add_f32_e32 v116, 1.0, v116
	v_add_f32_e32 v117, 1.0, v117
	v_add_f32_e32 v118, 1.0, v118
	v_add_f32_e32 v119, 1.0, v119
	v_add_f32_e32 v120, 1.0, v120
	v_add_f32_e32 v121, 1.0, v121
	v_add_f32_e32 v122, 1.0, v122
	v_add_f32_e32 v123, 1.0, v123
	v_rcp_f32_e32 v116, v116
	v_rcp_f32_e32 v117, v117
	v_rcp_f32_e32 v118, v118
	v_rcp_f32_e32 v119, v119
	v_rcp_f32_e32 v120, v120
	v_rcp_f32_e32 v121, v121
	v_rcp_f32_e32 v122, v122
	v_rcp_f32_e32 v123, v123
	v_pk_mul_f32 v[108:109], v[108:109], v[116:117]
	v_pk_mul_f32 v[110:111], v[110:111], v[118:119]
	v_pk_mul_f32 v[104:105], v[104:105], v[120:121]
	v_pk_mul_f32 v[106:107], v[106:107], v[122:123]
	v_pk_mul_f32 v[100:101], v[100:101], v[108:109]
	v_pk_mul_f32 v[102:103], v[102:103], v[110:111]
	v_pk_mul_f32 v[104:105], v[96:97], v[104:105]
	v_pk_mul_f32 v[106:107], v[98:99], v[106:107]
	v_cvt_pk_bf16_f32 v96, v100, v101
	v_cvt_pk_bf16_f32 v97, v102, v103
	v_cvt_pk_bf16_f32 v98, v104, v105
	v_cvt_pk_bf16_f32 v99, v106, v107
	global_store_dwordx4 v[112:113], v[96:99], off
	global_load_dwordx4 v[96:99], v[114:115], off
	s_nop 0
	global_load_dwordx4 v[100:103], v[114:115], off offset:16
	global_load_dwordx4 v[104:107], v[114:115], off offset:32
	global_load_dwordx4 v[108:111], v[114:115], off offset:48
	v_or_b32_e32 v112, 48, v148
	v_mad_i64_i32 v[114:115], s[8:9], v162, s58, v[144:145]
	v_ashrrev_i32_e32 v113, 31, v112
	s_waitcnt vmcnt(3)
	v_mov_b32_e32 v116, v97
	v_mov_b32_e32 v117, v98
	v_mov_b32_e32 v97, v99
	s_waitcnt vmcnt(2)
	v_mov_b32_e32 v98, v101
	v_mov_b32_e32 v99, v102
	v_mov_b32_e32 v101, v103
	s_waitcnt vmcnt(1)
	v_add_f32_e32 v102, v104, v105
	v_add_f32_e32 v104, v106, v107
	s_waitcnt vmcnt(0)
	v_mov_b32_e32 v103, v110
	v_mov_b32_e32 v105, v111
	v_pk_add_f32 v[96:97], v[116:117], v[96:97]
	v_pk_add_f32 v[98:99], v[98:99], v[100:101]
	v_pk_add_f32 v[100:101], v[102:103], v[104:105]
	v_add_f32_e32 v102, v96, v97
	v_pk_add_f32 v[96:97], v[98:99], v[98:99] op_sel:[0,1] op_sel_hi:[1,0]
	v_mov_b32_e32 v107, v108
	v_add_f32_e32 v106, 0, v102
	v_mov_b32_e32 v97, v109
	v_pk_add_f32 v[96:97], v[106:107], v[96:97]
	v_lshlrev_b64 v[98:99], 6, v[112:113]
	v_pk_add_f32 v[96:97], v[96:97], v[100:101]
	v_lshl_add_u64 v[98:99], s[18:19], 0, v[98:99]
	v_add_f32_e32 v96, v96, v97
	v_fmamk_f32 v96, v96, 0x3a800000, v161
	v_mul_f32_e32 v97, 0x4b800000, v96
	v_cmp_gt_f32_e32 vcc, s57, v96
	s_nop 1
	v_cndmask_b32_e32 v96, v96, v97, vcc
	v_rsq_f32_e32 v100, v96
	v_lshl_add_u64 v[96:97], v[114:115], 0, v[146:147]
	v_mul_f32_e32 v101, 0x45800000, v100
	v_cndmask_b32_e32 v100, v100, v101, vcc
	v_pk_mul_f32 v[92:93], v[92:93], v[100:101] op_sel_hi:[1,0]
	v_pk_mul_f32 v[94:95], v[94:95], v[100:101] op_sel_hi:[1,0]
	v_pk_mul_f32 v[88:89], v[88:89], v[100:101] op_sel_hi:[1,0]
	v_pk_mul_f32 v[90:91], v[90:91], v[100:101] op_sel_hi:[1,0]
	v_pk_mul_f32 v[84:85], v[84:85], v[100:101] op_sel_hi:[1,0]
	v_pk_mul_f32 v[86:87], v[86:87], v[100:101] op_sel_hi:[1,0]
	v_pk_mul_f32 v[80:81], v[80:81], v[100:101] op_sel_hi:[1,0]
	v_pk_mul_f32 v[82:83], v[82:83], v[100:101] op_sel_hi:[1,0]
	v_mul_f32_e32 v100, 0xbfb8aa3b, v92
	v_mul_f32_e32 v101, 0xbfb8aa3b, v93
	v_mul_f32_e32 v102, 0xbfb8aa3b, v94
	v_mul_f32_e32 v103, 0xbfb8aa3b, v95
	v_mul_f32_e32 v104, 0xbfb8aa3b, v88
	v_mul_f32_e32 v105, 0xbfb8aa3b, v89
	v_mul_f32_e32 v106, 0xbfb8aa3b, v90
	v_mul_f32_e32 v107, 0xbfb8aa3b, v91
	v_exp_f32_e32 v100, v100
	v_exp_f32_e32 v101, v101
	v_exp_f32_e32 v102, v102
	v_exp_f32_e32 v103, v103
	v_exp_f32_e32 v104, v104
	v_exp_f32_e32 v105, v105
	v_exp_f32_e32 v106, v106
	v_exp_f32_e32 v107, v107
	v_add_f32_e32 v100, 1.0, v100
	v_add_f32_e32 v101, 1.0, v101
	v_add_f32_e32 v102, 1.0, v102
	v_add_f32_e32 v103, 1.0, v103
	v_add_f32_e32 v104, 1.0, v104
	v_add_f32_e32 v105, 1.0, v105
	v_add_f32_e32 v106, 1.0, v106
	v_add_f32_e32 v107, 1.0, v107
	v_rcp_f32_e32 v100, v100
	v_rcp_f32_e32 v101, v101
	v_rcp_f32_e32 v102, v102
	v_rcp_f32_e32 v103, v103
	v_rcp_f32_e32 v104, v104
	v_rcp_f32_e32 v105, v105
	v_rcp_f32_e32 v106, v106
	v_rcp_f32_e32 v107, v107
	v_pk_mul_f32 v[92:93], v[92:93], v[100:101]
	v_pk_mul_f32 v[94:95], v[94:95], v[102:103]
	v_pk_mul_f32 v[88:89], v[88:89], v[104:105]
	v_pk_mul_f32 v[90:91], v[90:91], v[106:107]
	v_pk_mul_f32 v[84:85], v[84:85], v[92:93]
	v_pk_mul_f32 v[86:87], v[86:87], v[94:95]
	v_pk_mul_f32 v[88:89], v[80:81], v[88:89]
	v_pk_mul_f32 v[90:91], v[82:83], v[90:91]
	v_cvt_pk_bf16_f32 v80, v84, v85
	v_cvt_pk_bf16_f32 v81, v86, v87
	v_cvt_pk_bf16_f32 v82, v88, v89
	v_cvt_pk_bf16_f32 v83, v90, v91
	global_store_dwordx4 v[96:97], v[80:83], off
	global_load_dwordx4 v[80:83], v[98:99], off
	s_nop 0
	global_load_dwordx4 v[84:87], v[98:99], off offset:16
	global_load_dwordx4 v[88:91], v[98:99], off offset:32
	global_load_dwordx4 v[92:95], v[98:99], off offset:48
	v_add_u32_e32 v96, 0x80, v148
	v_mad_i64_i32 v[98:99], s[8:9], v112, s58, v[144:145]
	v_ashrrev_i32_e32 v97, 31, v96
	s_waitcnt vmcnt(3)
; __device__ __forceinline__ float sigmoidf_(float v) { return __builtin_amdgcn_rcpf(1.f + __builtin_amdgcn_exp2f(-v * LOG2E)); }
; __device__ __forceinline__ v4u pack8(f32x4 a, f32x4 b) { v4u r; r.x = cvt_pk_bf16(a[0], a[1]); r.y = cvt_pk_bf16(a[2], a[3]); r.z = cvt_pk_bf16(b[0], b[1]); r.w = cvt_pk_bf16(b[2], b[3]); return r; }
;     __device__ __forceinline__ void operator()(const f32x4 (&acc)[2][2][4][2], const Unit& u, int wr, int wc, int fr, int fq) const {
;     ...
;         for (int ai = 0; ai < 2; ++ai)
; #pragma unroll
;             for (int m = 0; m < 4; ++m) {
;                 const int row = row0 + ai * 128 + m * 16;
;                 float sq = 0.f;
; #pragma unroll
;                 for (int k = 0; k < 4; ++k) { const f32x4 p = *(const f32x4*)(ss1 + (size_t)row * 16 + 4 * k); sq += (p[0] + p[1]) + (p[2] + p[3]); }
;                 const float rs = rsqrtf(sq * (1.f / 1024.f) + EPS);
;                 f32x4 o[2];
; #pragma unroll
;                 for (int n = 0; n < 2; ++n) {
;                     const f32x4 g = acc[ai][0][m][n] * rs, up = acc[ai][1][m][n] * rs;
; #pragma unroll
;                     for (int j = 0; j < 4; ++j) o[n][j] = g[j] * sigmoidf_(g[j]) * up[j];
;                 }
;                 *(v4u*)(H + (size_t)row * FF + col0) = pack8(o[0], o[1]);
;             }
	v_mov_b32_e32 v100, v81
	v_mov_b32_e32 v101, v82
	v_mov_b32_e32 v81, v83
	s_waitcnt vmcnt(2)
	v_mov_b32_e32 v82, v85
	v_mov_b32_e32 v83, v86
	v_mov_b32_e32 v85, v87
	s_waitcnt vmcnt(1)
	v_add_f32_e32 v86, v88, v89
	v_add_f32_e32 v88, v90, v91
	s_waitcnt vmcnt(0)
	v_mov_b32_e32 v87, v94
	v_mov_b32_e32 v89, v95
	v_pk_add_f32 v[80:81], v[100:101], v[80:81]
	v_pk_add_f32 v[82:83], v[82:83], v[84:85]
	v_pk_add_f32 v[84:85], v[86:87], v[88:89]
	v_add_f32_e32 v86, v80, v81
	v_pk_add_f32 v[80:81], v[82:83], v[82:83] op_sel:[0,1] op_sel_hi:[1,0]
	v_mov_b32_e32 v91, v92
	v_add_f32_e32 v90, 0, v86
	v_mov_b32_e32 v81, v93
	v_pk_add_f32 v[80:81], v[90:91], v[80:81]
	v_lshlrev_b64 v[82:83], 6, v[96:97]
	v_pk_add_f32 v[80:81], v[80:81], v[84:85]
	v_lshl_add_u64 v[82:83], s[18:19], 0, v[82:83]
	v_add_f32_e32 v80, v80, v81
	v_fmamk_f32 v80, v80, 0x3a800000, v161
	v_mul_f32_e32 v81, 0x4b800000, v80
	v_cmp_gt_f32_e32 vcc, s57, v80
	s_nop 1
	v_cndmask_b32_e32 v80, v80, v81, vcc
	v_rsq_f32_e32 v84, v80
	v_lshl_add_u64 v[80:81], v[98:99], 0, v[146:147]
	v_mul_f32_e32 v85, 0x45800000, v84
	v_cndmask_b32_e32 v84, v84, v85, vcc
	v_pk_mul_f32 v[76:77], v[76:77], v[84:85] op_sel_hi:[1,0]
	v_pk_mul_f32 v[78:79], v[78:79], v[84:85] op_sel_hi:[1,0]
	v_pk_mul_f32 v[72:73], v[72:73], v[84:85] op_sel_hi:[1,0]
	v_pk_mul_f32 v[74:75], v[74:75], v[84:85] op_sel_hi:[1,0]
	v_pk_mul_f32 v[68:69], v[68:69], v[84:85] op_sel_hi:[1,0]
	v_pk_mul_f32 v[70:71], v[70:71], v[84:85] op_sel_hi:[1,0]
	v_pk_mul_f32 v[64:65], v[64:65], v[84:85] op_sel_hi:[1,0]
	v_pk_mul_f32 v[66:67], v[66:67], v[84:85] op_sel_hi:[1,0]
	v_mul_f32_e32 v84, 0xbfb8aa3b, v76
	v_mul_f32_e32 v85, 0xbfb8aa3b, v77
	v_mul_f32_e32 v86, 0xbfb8aa3b, v78
	v_mul_f32_e32 v87, 0xbfb8aa3b, v79
	v_mul_f32_e32 v88, 0xbfb8aa3b, v72
	v_mul_f32_e32 v89, 0xbfb8aa3b, v73
	v_mul_f32_e32 v90, 0xbfb8aa3b, v74
	v_mul_f32_e32 v91, 0xbfb8aa3b, v75
	v_exp_f32_e32 v84, v84
	v_exp_f32_e32 v85, v85
	v_exp_f32_e32 v86, v86
	v_exp_f32_e32 v87, v87
	v_exp_f32_e32 v88, v88
	v_exp_f32_e32 v89, v89
	v_exp_f32_e32 v90, v90
	v_exp_f32_e32 v91, v91
	v_add_f32_e32 v84, 1.0, v84
	v_add_f32_e32 v85, 1.0, v85
	v_add_f32_e32 v86, 1.0, v86
	v_add_f32_e32 v87, 1.0, v87
	v_add_f32_e32 v88, 1.0, v88
	v_add_f32_e32 v89, 1.0, v89
	v_add_f32_e32 v90, 1.0, v90
	v_add_f32_e32 v91, 1.0, v91
	v_rcp_f32_e32 v84, v84
	v_rcp_f32_e32 v85, v85
	v_rcp_f32_e32 v86, v86
	v_rcp_f32_e32 v87, v87
	v_rcp_f32_e32 v88, v88
	v_rcp_f32_e32 v89, v89
	v_rcp_f32_e32 v90, v90
	v_rcp_f32_e32 v91, v91
	v_pk_mul_f32 v[76:77], v[76:77], v[84:85]
	v_pk_mul_f32 v[78:79], v[78:79], v[86:87]
	v_pk_mul_f32 v[72:73], v[72:73], v[88:89]
	v_pk_mul_f32 v[74:75], v[74:75], v[90:91]
	v_pk_mul_f32 v[68:69], v[68:69], v[76:77]
	v_pk_mul_f32 v[70:71], v[70:71], v[78:79]
	v_pk_mul_f32 v[72:73], v[64:65], v[72:73]
	v_pk_mul_f32 v[74:75], v[66:67], v[74:75]
	v_cvt_pk_bf16_f32 v64, v68, v69
	v_cvt_pk_bf16_f32 v65, v70, v71
	v_cvt_pk_bf16_f32 v66, v72, v73
	v_cvt_pk_bf16_f32 v67, v74, v75
	global_store_dwordx4 v[80:81], v[64:67], off
	s_cmp_lg_u32 s98, 0
	s_cbranch_scc1 .Lh7_tail
	global_load_dwordx4 v[64:67], v[82:83], off
	s_nop 0
	global_load_dwordx4 v[68:71], v[82:83], off offset:16
	global_load_dwordx4 v[72:75], v[82:83], off offset:32
	global_load_dwordx4 v[76:79], v[82:83], off offset:48
	v_add_u32_e32 v80, 0x90, v148
	v_mad_i64_i32 v[82:83], s[8:9], v96, s58, v[144:145]
	v_ashrrev_i32_e32 v81, 31, v80
	s_waitcnt vmcnt(3)
	v_mov_b32_e32 v84, v65
	v_mov_b32_e32 v85, v66
	v_mov_b32_e32 v65, v67
	s_waitcnt vmcnt(2)
	v_mov_b32_e32 v66, v69
	v_mov_b32_e32 v67, v70
	v_mov_b32_e32 v69, v71
	s_waitcnt vmcnt(1)
	v_add_f32_e32 v70, v72, v73
	v_add_f32_e32 v72, v74, v75
	s_waitcnt vmcnt(0)
	v_mov_b32_e32 v71, v78
	v_mov_b32_e32 v73, v79
	v_pk_add_f32 v[64:65], v[84:85], v[64:65]
	v_pk_add_f32 v[66:67], v[66:67], v[68:69]
	v_pk_add_f32 v[68:69], v[70:71], v[72:73]
	v_add_f32_e32 v70, v64, v65
	v_pk_add_f32 v[64:65], v[66:67], v[66:67] op_sel:[0,1] op_sel_hi:[1,0]
	v_mov_b32_e32 v75, v76
	v_add_f32_e32 v74, 0, v70
	v_mov_b32_e32 v65, v77
	v_pk_add_f32 v[64:65], v[74:75], v[64:65]
	v_lshlrev_b64 v[66:67], 6, v[80:81]
	v_pk_add_f32 v[64:65], v[64:65], v[68:69]
	v_lshl_add_u64 v[66:67], s[18:19], 0, v[66:67]
	v_add_f32_e32 v64, v64, v65
	v_fmamk_f32 v64, v64, 0x3a800000, v161
	v_mul_f32_e32 v65, 0x4b800000, v64
	v_cmp_gt_f32_e32 vcc, s57, v64
	s_nop 1
	v_cndmask_b32_e32 v64, v64, v65, vcc
	v_rsq_f32_e32 v68, v64
	v_lshl_add_u64 v[64:65], v[82:83], 0, v[146:147]
	v_mul_f32_e32 v69, 0x45800000, v68
	v_cndmask_b32_e32 v68, v68, v69, vcc
	v_pk_mul_f32 v[60:61], v[60:61], v[68:69] op_sel_hi:[1,0]
	v_pk_mul_f32 v[62:63], v[62:63], v[68:69] op_sel_hi:[1,0]
	v_pk_mul_f32 v[56:57], v[56:57], v[68:69] op_sel_hi:[1,0]
	v_pk_mul_f32 v[58:59], v[58:59], v[68:69] op_sel_hi:[1,0]
	v_pk_mul_f32 v[52:53], v[52:53], v[68:69] op_sel_hi:[1,0]
	v_pk_mul_f32 v[54:55], v[54:55], v[68:69] op_sel_hi:[1,0]
	v_pk_mul_f32 v[48:49], v[48:49], v[68:69] op_sel_hi:[1,0]
	v_pk_mul_f32 v[50:51], v[50:51], v[68:69] op_sel_hi:[1,0]
	v_mul_f32_e32 v68, 0xbfb8aa3b, v60
	v_mul_f32_e32 v69, 0xbfb8aa3b, v61
	v_mul_f32_e32 v70, 0xbfb8aa3b, v62
	v_mul_f32_e32 v71, 0xbfb8aa3b, v63
	v_mul_f32_e32 v72, 0xbfb8aa3b, v56
	v_mul_f32_e32 v73, 0xbfb8aa3b, v57
	v_mul_f32_e32 v74, 0xbfb8aa3b, v58
	v_mul_f32_e32 v75, 0xbfb8aa3b, v59
	v_exp_f32_e32 v68, v68
	v_exp_f32_e32 v69, v69
	v_exp_f32_e32 v70, v70
	v_exp_f32_e32 v71, v71
	v_exp_f32_e32 v72, v72
	v_exp_f32_e32 v73, v73
	v_exp_f32_e32 v74, v74
	v_exp_f32_e32 v75, v75
	v_add_f32_e32 v68, 1.0, v68
	v_add_f32_e32 v69, 1.0, v69
	v_add_f32_e32 v70, 1.0, v70
	v_add_f32_e32 v71, 1.0, v71
	v_add_f32_e32 v72, 1.0, v72
	v_add_f32_e32 v73, 1.0, v73
	v_add_f32_e32 v74, 1.0, v74
	v_add_f32_e32 v75, 1.0, v75
	v_rcp_f32_e32 v68, v68
	v_rcp_f32_e32 v69, v69
	v_rcp_f32_e32 v70, v70
	v_rcp_f32_e32 v71, v71
	v_rcp_f32_e32 v72, v72
	v_rcp_f32_e32 v73, v73
	v_rcp_f32_e32 v74, v74
	v_rcp_f32_e32 v75, v75
	v_pk_mul_f32 v[60:61], v[60:61], v[68:69]
	v_pk_mul_f32 v[62:63], v[62:63], v[70:71]
	v_pk_mul_f32 v[56:57], v[56:57], v[72:73]
	v_pk_mul_f32 v[58:59], v[58:59], v[74:75]
	v_pk_mul_f32 v[52:53], v[52:53], v[60:61]
	v_pk_mul_f32 v[54:55], v[54:55], v[62:63]
	v_pk_mul_f32 v[56:57], v[48:49], v[56:57]
	v_pk_mul_f32 v[58:59], v[50:51], v[58:59]
	v_cvt_pk_bf16_f32 v48, v52, v53
	v_cvt_pk_bf16_f32 v49, v54, v55
	v_cvt_pk_bf16_f32 v50, v56, v57
	v_cvt_pk_bf16_f32 v51, v58, v59
	global_store_dwordx4 v[64:65], v[48:51], off
	global_load_dwordx4 v[48:51], v[66:67], off
	s_nop 0
	global_load_dwordx4 v[52:55], v[66:67], off offset:16
	global_load_dwordx4 v[56:59], v[66:67], off offset:32
	global_load_dwordx4 v[60:63], v[66:67], off offset:48
	v_add_u32_e32 v64, 0xa0, v148
	v_mad_i64_i32 v[66:67], s[8:9], v80, s58, v[144:145]
	v_ashrrev_i32_e32 v65, 31, v64
	s_waitcnt vmcnt(3)
; __device__ __forceinline__ float sigmoidf_(float v) { return __builtin_amdgcn_rcpf(1.f + __builtin_amdgcn_exp2f(-v * LOG2E)); }
; __device__ __forceinline__ v4u pack8(f32x4 a, f32x4 b) { v4u r; r.x = cvt_pk_bf16(a[0], a[1]); r.y = cvt_pk_bf16(a[2], a[3]); r.z = cvt_pk_bf16(b[0], b[1]); r.w = cvt_pk_bf16(b[2], b[3]); return r; }
;     __device__ __forceinline__ void operator()(const f32x4 (&acc)[2][2][4][2], const Unit& u, int wr, int wc, int fr, int fq) const {
;     ...
;         for (int ai = 0; ai < 2; ++ai)
; #pragma unroll
;             for (int m = 0; m < 4; ++m) {
;                 const int row = row0 + ai * 128 + m * 16;
;                 float sq = 0.f;
; #pragma unroll
;                 for (int k = 0; k < 4; ++k) { const f32x4 p = *(const f32x4*)(ss1 + (size_t)row * 16 + 4 * k); sq += (p[0] + p[1]) + (p[2] + p[3]); }
;                 const float rs = rsqrtf(sq * (1.f / 1024.f) + EPS);
;                 f32x4 o[2];
; #pragma unroll
;                 for (int n = 0; n < 2; ++n) {
;                     const f32x4 g = acc[ai][0][m][n] * rs, up = acc[ai][1][m][n] * rs;
; #pragma unroll
;                     for (int j = 0; j < 4; ++j) o[n][j] = g[j] * sigmoidf_(g[j]) * up[j];
;                 }
;                 *(v4u*)(H + (size_t)row * FF + col0) = pack8(o[0], o[1]);
;             }
	v_mov_b32_e32 v68, v49
	v_mov_b32_e32 v69, v50
	v_mov_b32_e32 v49, v51
	s_waitcnt vmcnt(2)
	v_mov_b32_e32 v50, v53
	v_mov_b32_e32 v51, v54
	v_mov_b32_e32 v53, v55
	s_waitcnt vmcnt(1)
	v_add_f32_e32 v54, v56, v57
	v_add_f32_e32 v56, v58, v59
	s_waitcnt vmcnt(0)
	v_mov_b32_e32 v55, v62
	v_mov_b32_e32 v57, v63
	v_pk_add_f32 v[48:49], v[68:69], v[48:49]
	v_pk_add_f32 v[50:51], v[50:51], v[52:53]
	v_pk_add_f32 v[52:53], v[54:55], v[56:57]
	v_add_f32_e32 v54, v48, v49
	v_pk_add_f32 v[48:49], v[50:51], v[50:51] op_sel:[0,1] op_sel_hi:[1,0]
	v_mov_b32_e32 v59, v60
	v_add_f32_e32 v58, 0, v54
	v_mov_b32_e32 v49, v61
	v_pk_add_f32 v[48:49], v[58:59], v[48:49]
	v_lshlrev_b64 v[50:51], 6, v[64:65]
	v_pk_add_f32 v[48:49], v[48:49], v[52:53]
	v_lshl_add_u64 v[50:51], s[18:19], 0, v[50:51]
	v_add_f32_e32 v48, v48, v49
	v_fmamk_f32 v48, v48, 0x3a800000, v161
	v_mul_f32_e32 v49, 0x4b800000, v48
	v_cmp_gt_f32_e32 vcc, s57, v48
	s_nop 1
	v_cndmask_b32_e32 v48, v48, v49, vcc
	v_rsq_f32_e32 v52, v48
	v_lshl_add_u64 v[48:49], v[66:67], 0, v[146:147]
	v_mul_f32_e32 v53, 0x45800000, v52
	v_cndmask_b32_e32 v52, v52, v53, vcc
	v_pk_mul_f32 v[44:45], v[44:45], v[52:53] op_sel_hi:[1,0]
	v_pk_mul_f32 v[46:47], v[46:47], v[52:53] op_sel_hi:[1,0]
	v_pk_mul_f32 v[40:41], v[40:41], v[52:53] op_sel_hi:[1,0]
	v_pk_mul_f32 v[42:43], v[42:43], v[52:53] op_sel_hi:[1,0]
	v_pk_mul_f32 v[36:37], v[36:37], v[52:53] op_sel_hi:[1,0]
	v_pk_mul_f32 v[38:39], v[38:39], v[52:53] op_sel_hi:[1,0]
	v_pk_mul_f32 v[32:33], v[32:33], v[52:53] op_sel_hi:[1,0]
	v_pk_mul_f32 v[34:35], v[34:35], v[52:53] op_sel_hi:[1,0]
	v_mul_f32_e32 v52, 0xbfb8aa3b, v44
	v_mul_f32_e32 v53, 0xbfb8aa3b, v45
	v_mul_f32_e32 v54, 0xbfb8aa3b, v46
	v_mul_f32_e32 v55, 0xbfb8aa3b, v47
	v_mul_f32_e32 v56, 0xbfb8aa3b, v40
	v_mul_f32_e32 v57, 0xbfb8aa3b, v41
	v_mul_f32_e32 v58, 0xbfb8aa3b, v42
	v_mul_f32_e32 v59, 0xbfb8aa3b, v43
	v_exp_f32_e32 v52, v52
	v_exp_f32_e32 v53, v53
	v_exp_f32_e32 v54, v54
	v_exp_f32_e32 v55, v55
	v_exp_f32_e32 v56, v56
	v_exp_f32_e32 v57, v57
	v_exp_f32_e32 v58, v58
	v_exp_f32_e32 v59, v59
	v_add_f32_e32 v52, 1.0, v52
	v_add_f32_e32 v53, 1.0, v53
	v_add_f32_e32 v54, 1.0, v54
	v_add_f32_e32 v55, 1.0, v55
	v_add_f32_e32 v56, 1.0, v56
	v_add_f32_e32 v57, 1.0, v57
	v_add_f32_e32 v58, 1.0, v58
	v_add_f32_e32 v59, 1.0, v59
	v_rcp_f32_e32 v52, v52
	v_rcp_f32_e32 v53, v53
	v_rcp_f32_e32 v54, v54
	v_rcp_f32_e32 v55, v55
	v_rcp_f32_e32 v56, v56
	v_rcp_f32_e32 v57, v57
	v_rcp_f32_e32 v58, v58
	v_rcp_f32_e32 v59, v59
	v_pk_mul_f32 v[44:45], v[44:45], v[52:53]
	v_pk_mul_f32 v[46:47], v[46:47], v[54:55]
	v_pk_mul_f32 v[40:41], v[40:41], v[56:57]
	v_pk_mul_f32 v[42:43], v[42:43], v[58:59]
	v_pk_mul_f32 v[36:37], v[36:37], v[44:45]
	v_pk_mul_f32 v[38:39], v[38:39], v[46:47]
	v_pk_mul_f32 v[40:41], v[32:33], v[40:41]
	v_pk_mul_f32 v[42:43], v[34:35], v[42:43]
	v_cvt_pk_bf16_f32 v32, v36, v37
	v_cvt_pk_bf16_f32 v33, v38, v39
	v_cvt_pk_bf16_f32 v34, v40, v41
	v_cvt_pk_bf16_f32 v35, v42, v43
	global_store_dwordx4 v[48:49], v[32:35], off
	global_load_dwordx4 v[32:35], v[50:51], off
	s_nop 0
	global_load_dwordx4 v[36:39], v[50:51], off offset:16
	global_load_dwordx4 v[40:43], v[50:51], off offset:32
	global_load_dwordx4 v[44:47], v[50:51], off offset:48
	v_add_u32_e32 v48, 0xb0, v148
	v_mad_i64_i32 v[50:51], s[8:9], v64, s58, v[144:145]
	v_ashrrev_i32_e32 v49, 31, v48
	s_waitcnt vmcnt(3)
	v_mov_b32_e32 v52, v33
	v_mov_b32_e32 v53, v34
	v_mov_b32_e32 v33, v35
	s_waitcnt vmcnt(2)
	v_mov_b32_e32 v34, v37
	v_mov_b32_e32 v35, v38
	v_mov_b32_e32 v37, v39
	s_waitcnt vmcnt(1)
	v_add_f32_e32 v38, v40, v41
	v_add_f32_e32 v40, v42, v43
	s_waitcnt vmcnt(0)
; #define PG8_BAR __builtin_amdgcn_s_barrier()
; __device__ __forceinline__ float sigmoidf_(float v) { return __builtin_amdgcn_rcpf(1.f + __builtin_amdgcn_exp2f(-v * LOG2E)); }
; __device__ __forceinline__ v4u pack8(f32x4 a, f32x4 b) { v4u r; r.x = cvt_pk_bf16(a[0], a[1]); r.y = cvt_pk_bf16(a[2], a[3]); r.z = cvt_pk_bf16(b[0], b[1]); r.w = cvt_pk_bf16(b[2], b[3]); return r; }
; template <class Epi, class Sched, bool ALIGN_EPI = false, bool SP2 = false>
; __device__ __forceinline__ void gemm_phase(PG8_LAS unsigned char* lds, const Gemm g, const Sched& S, const Epi& E) {
;     ...
;         if (!has_next) break;
; #pragma unroll
;         for (int a = 0; a < 2; ++a)
; #pragma unroll
;             for (int b = 0; b < 2; ++b)
; #pragma unroll
;                 for (int m = 0; m < 4; ++m)
; #pragma unroll
;                     for (int n = 0; n < 2; ++n) acc[a][b][m][n] = (f32x4){0.f, 0.f, 0.f, 0.f};
;         cur = nxt; cA = nA; cB = nB; ++ui;
;         if constexpr (ALIGN_EPI) { if (wr == 1) PG8_BAR; }
;     __device__ __forceinline__ void operator()(const f32x4 (&acc)[2][2][4][2], const Unit& u, int wr, int wc, int fr, int fq) const {
;         const int row0 = u.pm * 256 + wr * 64 + fr, col0 = u.pn * 128 + wc * 32 + 8 * fq;
; #pragma unroll
;         for (int ai = 0; ai < 2; ++ai)
; #pragma unroll
;             for (int m = 0; m < 4; ++m) {
;                 const int row = row0 + ai * 128 + m * 16;
;                 float sq = 0.f;
; #pragma unroll
;                 for (int k = 0; k < 4; ++k) { const f32x4 p = *(const f32x4*)(ss1 + (size_t)row * 16 + 4 * k); sq += (p[0] + p[1]) + (p[2] + p[3]); }
;                 const float rs = rsqrtf(sq * (1.f / 1024.f) + EPS);
;                 f32x4 o[2];
; #pragma unroll
;                 for (int n = 0; n < 2; ++n) {
;                     const f32x4 g = acc[ai][0][m][n] * rs, up = acc[ai][1][m][n] * rs;
; #pragma unroll
;                     for (int j = 0; j < 4; ++j) o[n][j] = g[j] * sigmoidf_(g[j]) * up[j];
;                 }
;                 *(v4u*)(H + (size_t)row * FF + col0) = pack8(o[0], o[1]);
	v_mov_b32_e32 v39, v46
	v_mov_b32_e32 v41, v47
	v_pk_add_f32 v[32:33], v[52:53], v[32:33]
	v_pk_add_f32 v[34:35], v[34:35], v[36:37]
	v_pk_add_f32 v[36:37], v[38:39], v[40:41]
	v_add_f32_e32 v38, v32, v33
	v_pk_add_f32 v[32:33], v[34:35], v[34:35] op_sel:[0,1] op_sel_hi:[1,0]
	v_mov_b32_e32 v43, v44
	v_add_f32_e32 v42, 0, v38
	v_mov_b32_e32 v33, v45
	v_pk_add_f32 v[32:33], v[42:43], v[32:33]
	v_lshlrev_b64 v[34:35], 6, v[48:49]
	v_pk_add_f32 v[32:33], v[32:33], v[36:37]
	v_lshl_add_u64 v[34:35], s[18:19], 0, v[34:35]
	v_add_f32_e32 v32, v32, v33
	v_fmamk_f32 v32, v32, 0x3a800000, v161
	v_mul_f32_e32 v33, 0x4b800000, v32
	v_cmp_gt_f32_e32 vcc, s57, v32
	s_nop 1
	v_cndmask_b32_e32 v32, v32, v33, vcc
	v_rsq_f32_e32 v36, v32
	v_lshl_add_u64 v[32:33], v[50:51], 0, v[146:147]
	v_mul_f32_e32 v37, 0x45800000, v36
	v_cndmask_b32_e32 v36, v36, v37, vcc
	v_pk_mul_f32 v[28:29], v[28:29], v[36:37] op_sel_hi:[1,0]
	v_pk_mul_f32 v[30:31], v[30:31], v[36:37] op_sel_hi:[1,0]
	v_pk_mul_f32 v[24:25], v[24:25], v[36:37] op_sel_hi:[1,0]
	v_pk_mul_f32 v[26:27], v[26:27], v[36:37] op_sel_hi:[1,0]
	v_pk_mul_f32 v[20:21], v[20:21], v[36:37] op_sel_hi:[1,0]
	v_pk_mul_f32 v[22:23], v[22:23], v[36:37] op_sel_hi:[1,0]
	v_pk_mul_f32 v[16:17], v[16:17], v[36:37] op_sel_hi:[1,0]
	v_pk_mul_f32 v[18:19], v[18:19], v[36:37] op_sel_hi:[1,0]
	v_mul_f32_e32 v36, 0xbfb8aa3b, v28
	v_mul_f32_e32 v37, 0xbfb8aa3b, v29
	v_mul_f32_e32 v38, 0xbfb8aa3b, v30
	v_mul_f32_e32 v39, 0xbfb8aa3b, v31
	v_mul_f32_e32 v40, 0xbfb8aa3b, v24
	v_mul_f32_e32 v41, 0xbfb8aa3b, v25
	v_mul_f32_e32 v42, 0xbfb8aa3b, v26
	v_mul_f32_e32 v43, 0xbfb8aa3b, v27
	v_exp_f32_e32 v36, v36
	v_exp_f32_e32 v37, v37
	v_exp_f32_e32 v38, v38
	v_exp_f32_e32 v39, v39
	v_exp_f32_e32 v40, v40
	v_exp_f32_e32 v41, v41
	v_exp_f32_e32 v42, v42
	v_exp_f32_e32 v43, v43
	v_add_f32_e32 v36, 1.0, v36
	v_add_f32_e32 v37, 1.0, v37
	v_add_f32_e32 v38, 1.0, v38
	v_add_f32_e32 v39, 1.0, v39
	v_add_f32_e32 v40, 1.0, v40
	v_add_f32_e32 v41, 1.0, v41
	v_add_f32_e32 v42, 1.0, v42
	v_add_f32_e32 v43, 1.0, v43
	v_rcp_f32_e32 v36, v36
	v_rcp_f32_e32 v37, v37
	v_rcp_f32_e32 v38, v38
	v_rcp_f32_e32 v39, v39
	v_rcp_f32_e32 v40, v40
	v_rcp_f32_e32 v41, v41
	v_rcp_f32_e32 v42, v42
	v_rcp_f32_e32 v43, v43
	v_pk_mul_f32 v[28:29], v[28:29], v[36:37]
	v_pk_mul_f32 v[30:31], v[30:31], v[38:39]
	v_pk_mul_f32 v[24:25], v[24:25], v[40:41]
	v_pk_mul_f32 v[26:27], v[26:27], v[42:43]
	v_pk_mul_f32 v[20:21], v[20:21], v[28:29]
	v_pk_mul_f32 v[22:23], v[22:23], v[30:31]
	v_pk_mul_f32 v[24:25], v[16:17], v[24:25]
	v_pk_mul_f32 v[26:27], v[18:19], v[26:27]
	v_cvt_pk_bf16_f32 v16, v20, v21
	v_cvt_pk_bf16_f32 v17, v22, v23
	v_cvt_pk_bf16_f32 v18, v24, v25
	v_cvt_pk_bf16_f32 v19, v26, v27
	global_store_dwordx4 v[32:33], v[16:19], off
	global_load_dwordx4 v[16:19], v[34:35], off
	s_nop 0
	global_load_dwordx4 v[20:23], v[34:35], off offset:16
	global_load_dwordx4 v[24:27], v[34:35], off offset:32
	global_load_dwordx4 v[28:31], v[34:35], off offset:48
	s_andn2_b64 vcc, exec, s[6:7]
	s_mov_b64 s[6:7], -1
	s_waitcnt vmcnt(3)
	v_mov_b32_e32 v32, v17
	v_mov_b32_e32 v33, v18
	v_mov_b32_e32 v17, v19
	s_waitcnt vmcnt(2)
	v_mov_b32_e32 v18, v21
	v_mov_b32_e32 v19, v22
	v_mov_b32_e32 v21, v23
	s_waitcnt vmcnt(1)
	v_add_f32_e32 v22, v24, v25
	v_add_f32_e32 v24, v26, v27
	s_waitcnt vmcnt(0)
	v_mov_b32_e32 v23, v30
	v_mov_b32_e32 v25, v31
	v_pk_add_f32 v[16:17], v[32:33], v[16:17]
	v_pk_add_f32 v[18:19], v[18:19], v[20:21]
	v_pk_add_f32 v[20:21], v[22:23], v[24:25]
	v_add_f32_e32 v22, v16, v17
	v_pk_add_f32 v[16:17], v[18:19], v[18:19] op_sel:[0,1] op_sel_hi:[1,0]
	v_mov_b32_e32 v27, v28
	v_add_f32_e32 v26, 0, v22
	v_mov_b32_e32 v17, v29
	v_pk_add_f32 v[16:17], v[26:27], v[16:17]
	s_nop 0
	v_pk_add_f32 v[16:17], v[16:17], v[20:21]
	s_nop 0
	v_add_f32_e32 v16, v16, v17
	v_fmamk_f32 v16, v16, 0x3a800000, v161
	v_mul_f32_e32 v17, 0x4b800000, v16
	v_cmp_gt_f32_e64 s[8:9], s57, v16
	s_nop 1
	v_cndmask_b32_e64 v16, v16, v17, s[8:9]
	v_rsq_f32_e32 v18, v16
	v_mad_i64_i32 v[16:17], s[46:47], v48, s58, v[144:145]
	v_lshl_add_u64 v[16:17], v[16:17], 0, v[146:147]
	v_mul_f32_e32 v19, 0x45800000, v18
	v_cndmask_b32_e64 v18, v18, v19, s[8:9]
	v_pk_mul_f32 v[12:13], v[12:13], v[18:19] op_sel_hi:[1,0]
	v_pk_mul_f32 v[14:15], v[14:15], v[18:19] op_sel_hi:[1,0]
	v_pk_mul_f32 v[8:9], v[8:9], v[18:19] op_sel_hi:[1,0]
	v_pk_mul_f32 v[10:11], v[10:11], v[18:19] op_sel_hi:[1,0]
	v_pk_mul_f32 v[4:5], v[4:5], v[18:19] op_sel_hi:[1,0]
	v_pk_mul_f32 v[6:7], v[6:7], v[18:19] op_sel_hi:[1,0]
	v_pk_mul_f32 v[0:1], v[0:1], v[18:19] op_sel_hi:[1,0]
	v_pk_mul_f32 v[2:3], v[2:3], v[18:19] op_sel_hi:[1,0]
	v_mul_f32_e32 v18, 0xbfb8aa3b, v12
	v_mul_f32_e32 v19, 0xbfb8aa3b, v13
	v_mul_f32_e32 v20, 0xbfb8aa3b, v14
	v_mul_f32_e32 v21, 0xbfb8aa3b, v15
	v_mul_f32_e32 v22, 0xbfb8aa3b, v8
	v_mul_f32_e32 v23, 0xbfb8aa3b, v9
	v_mul_f32_e32 v24, 0xbfb8aa3b, v10
	v_mul_f32_e32 v25, 0xbfb8aa3b, v11
	v_exp_f32_e32 v18, v18
	v_exp_f32_e32 v19, v19
	v_exp_f32_e32 v20, v20
	v_exp_f32_e32 v21, v21
	v_exp_f32_e32 v22, v22
	v_exp_f32_e32 v23, v23
	v_exp_f32_e32 v24, v24
	v_exp_f32_e32 v25, v25
	v_add_f32_e32 v18, 1.0, v18
	v_add_f32_e32 v19, 1.0, v19
	v_add_f32_e32 v20, 1.0, v20
	v_add_f32_e32 v21, 1.0, v21
	v_add_f32_e32 v22, 1.0, v22
	v_add_f32_e32 v23, 1.0, v23
	v_add_f32_e32 v24, 1.0, v24
	v_add_f32_e32 v25, 1.0, v25
	v_rcp_f32_e32 v18, v18
	v_rcp_f32_e32 v19, v19
	v_rcp_f32_e32 v20, v20
	v_rcp_f32_e32 v21, v21
	v_rcp_f32_e32 v22, v22
	v_rcp_f32_e32 v23, v23
	v_rcp_f32_e32 v24, v24
	v_rcp_f32_e32 v25, v25
	v_pk_mul_f32 v[12:13], v[12:13], v[18:19]
	v_pk_mul_f32 v[14:15], v[14:15], v[20:21]
	v_pk_mul_f32 v[8:9], v[8:9], v[22:23]
	v_pk_mul_f32 v[10:11], v[10:11], v[24:25]
	v_pk_mul_f32 v[4:5], v[4:5], v[12:13]
	v_pk_mul_f32 v[6:7], v[6:7], v[14:15]
	v_pk_mul_f32 v[8:9], v[0:1], v[8:9]
	v_pk_mul_f32 v[10:11], v[2:3], v[10:11]
	v_cvt_pk_bf16_f32 v0, v4, v5
	v_cvt_pk_bf16_f32 v1, v6, v7
	v_cvt_pk_bf16_f32 v2, v8, v9
	v_cvt_pk_bf16_f32 v3, v10, v11
	global_store_dwordx4 v[16:17], v[0:3], off
	s_cbranch_vccnz .LBB0_1474
	s_andn2_b64 vcc, exec, s[10:11]
	s_cbranch_vccnz .LBB0_1473
	s_barrier
	s_branch .LBB0_1473
.Lh7_tail:
	s_andn2_b64 vcc, exec, s[6:7]
	s_mov_b64 s[6:7], -1
	s_cbranch_vccnz .LBB0_1474
	s_andn2_b64 vcc, exec, s[10:11]
	s_cbranch_vccnz .LBB0_1473
	s_barrier
	s_branch .LBB0_1473
